# GEMM K-loop: B-fragment LDS reads of phases 1/5 issued one phase earlier (after the mid barrier of phases 8/4)
# baseline (speedup 1.0000x reference)
; #define PG8_STAGE(bufoff, gbase, voff) do { _Pragma("unroll") for (int _i = 0; _i < 2; ++_i) \
;         __builtin_amdgcn_global_load_lds((const unsigned*)((const char*)(gbase) + (voff)[_i]), (LAS unsigned*)(lds + (bufoff) + ldsw + _i * 8192), 16, 0, 0); } while (0)
; #define PG8_LDA(dst, b, h) do { _Pragma("unroll") for (int m = 0; m < 4; ++m) _Pragma("unroll") for (int k = 0; k < 2; ++k) dst[m][k] = *(const LAS bf16x8*)(lds + PG8_SA(b, h) + aoff + m * 2048 + k * 1024); } while (0)
; #define PG8_LDB(dst, b, h) do { _Pragma("unroll") for (int n = 0; n < 2; ++n) _Pragma("unroll") for (int k = 0; k < 2; ++k) dst[n][k] = *(const LAS bf16x8*)(lds + PG8_SB(b, h) + boff + n * 2048 + k * 1024); } while (0)
; template <class Epi, class Sched>
; __device__ __forceinline__ void gemm_phase(LAS unsigned char* lds, const Gemm g, const Sched& S, const Epi& E) {
;     ...
;                 for (int n = 0; n < 2; ++n) acc[a][b][m][n] = (f32x4){0.f, 0.f, 0.f, 0.f};
;     bf16x8 At[4][2], B0[2][2], B1[2][2];
;     const char* cA = (const char*)g.A + (size_t)cur.pm * tstep; const char* cB = (const char*)g.Bt + (size_t)cur.pn * tstep;
;     S.a_ready(cur);
;     PG8_STAGE(PG8_SB(0, 0), cB, voffB); PG8_STAGE(PG8_SA(0, 0), cA, voffA); PG8_STAGE(PG8_SB(0, 1), cB + hstep, voffB); PG8_STAGE(PG8_SA(0, 1), cA + hstep, voffA);
;     if (wr == 1) PG8_BAR;
;     PG8_WAIT_V(4); PG8_BAR;
;     PG8_STAGE(PG8_SB(1, 0), cB + kstep, voffB); PG8_STAGE(PG8_SA(1, 0), cA + kstep, voffA); PG8_STAGE(PG8_SB(1, 1), cB + hstep + kstep, voffB);
;     PG8_WAIT_V(6); PG8_BAR;
;     for (;;) {
;         const bool has_next = S.next(ui + 1, nxt);
;         const char* nA = has_next ? (const char*)g.A + (size_t)nxt.pm * tstep : cA; const char* nB = has_next ? (const char*)g.Bt + (size_t)nxt.pn * tstep : cB;
;         for (int t = 0; t < nt; t += 2) {
;             const bool last = (t == nt - 2);
;             const char* a1 = cA + (size_t)(t + 1) * kstep;
;             const char* a2 = last ? nA : cA + (size_t)(t + 2) * kstep; const char* b2 = last ? nB : cB + (size_t)(t + 2) * kstep;
;             const char* a3 = a2 + kstep; const char* b3 = b2 + kstep;
;             if (last && has_next) S.a_ready(nxt);
;             PG8_LDB(B0, 0, 0); PG8_SCHED; PG8_LDA(At, 0, 0); PG8_STAGE(PG8_SA(1, 1), a1 + hstep, voffA);
;             PG8_WAIT_L(8); PG8_BAR; PG8_WAIT_L(0); PG8_MMA(0, 0, At, B0); PG8_BAR; PG8_SCHED;
.LBB0_186:
	s_ashr_i32 s41, s40, 31
	s_lshl_b64 s[16:17], s[40:41], 19
	v_cmp_lt_i64_e32 vcc, s[42:43], v[138:139]
	s_add_u32 s42, s76, s16
	s_addc_u32 s43, s77, s17
	s_and_b64 s[16:17], vcc, exec
	s_cselect_b32 s41, s43, s71
	s_cselect_b32 s78, s42, s70
	s_ashr_i32 s1, s0, 31
	s_lshl_b64 s[16:17], s[0:1], 19
	s_add_u32 s88, s6, s16
	s_addc_u32 s89, s7, s17
	s_and_b64 s[16:17], vcc, exec
	s_cselect_b32 s1, s89, s67
	s_cselect_b32 s16, s88, s66
	s_add_u32 s72, s70, 0x40080
	s_addc_u32 s73, s71, 0
	s_add_u32 s17, s66, 0x100
	v_mov_b32_e32 v0, 0
	s_addc_u32 s18, s67, 0
	s_mov_b32 s19, -2
	v_mov_b32_e32 v1, v0
	v_mov_b32_e32 v2, v0
	v_mov_b32_e32 v3, v0
	v_mov_b32_e32 v4, v0
	v_mov_b32_e32 v5, v0
	v_mov_b32_e32 v6, v0
	v_mov_b32_e32 v7, v0
	v_mov_b32_e32 v10, v0
	v_mov_b32_e32 v11, v0
	v_mov_b32_e32 v12, v0
	v_mov_b32_e32 v13, v0
	v_mov_b32_e32 v14, v0
	v_mov_b32_e32 v15, v0
	v_mov_b32_e32 v16, v0
	v_mov_b32_e32 v17, v0
	v_mov_b32_e32 v26, v0
	v_mov_b32_e32 v27, v0
	v_mov_b32_e32 v28, v0
	v_mov_b32_e32 v29, v0
	v_mov_b32_e32 v30, v0
	v_mov_b32_e32 v31, v0
	v_mov_b32_e32 v32, v0
	v_mov_b32_e32 v33, v0
	v_mov_b32_e32 v42, v0
	v_mov_b32_e32 v43, v0
	v_mov_b32_e32 v44, v0
	v_mov_b32_e32 v45, v0
	v_mov_b32_e32 v46, v0
	v_mov_b32_e32 v47, v0
	v_mov_b32_e32 v48, v0
	v_mov_b32_e32 v49, v0
	v_mov_b32_e32 v18, v0
	v_mov_b32_e32 v19, v0
	v_mov_b32_e32 v20, v0
	v_mov_b32_e32 v21, v0
	v_mov_b32_e32 v22, v0
	v_mov_b32_e32 v23, v0
	v_mov_b32_e32 v24, v0
	v_mov_b32_e32 v25, v0
	v_mov_b32_e32 v34, v0
	v_mov_b32_e32 v35, v0
	v_mov_b32_e32 v36, v0
	v_mov_b32_e32 v37, v0
	v_mov_b32_e32 v38, v0
	v_mov_b32_e32 v39, v0
	v_mov_b32_e32 v40, v0
	v_mov_b32_e32 v41, v0
	v_mov_b32_e32 v50, v0
	v_mov_b32_e32 v51, v0
	v_mov_b32_e32 v52, v0
	v_mov_b32_e32 v53, v0
	v_mov_b32_e32 v54, v0
	v_mov_b32_e32 v55, v0
	v_mov_b32_e32 v56, v0
	v_mov_b32_e32 v57, v0
	v_mov_b32_e32 v58, v0
	v_mov_b32_e32 v59, v0
	v_mov_b32_e32 v60, v0
	v_mov_b32_e32 v61, v0
	v_mov_b32_e32 v62, v0
	v_mov_b32_e32 v63, v0
	v_mov_b32_e32 v64, v0
	v_mov_b32_e32 v65, v0
	v_mov_b32_e32 v66, v0
	v_mov_b32_e32 v67, v0
	v_mov_b32_e32 v68, v0
	v_mov_b32_e32 v69, v0
	v_mov_b32_e32 v70, v0
	v_mov_b32_e32 v71, v0
	v_mov_b32_e32 v72, v0
	v_mov_b32_e32 v73, v0
	v_mov_b32_e32 v74, v0
	v_mov_b32_e32 v75, v0
	v_mov_b32_e32 v76, v0
	v_mov_b32_e32 v77, v0
	v_mov_b32_e32 v82, v0
	v_mov_b32_e32 v83, v0
	v_mov_b32_e32 v84, v0
	v_mov_b32_e32 v85, v0
	v_mov_b32_e32 v90, v0
	v_mov_b32_e32 v91, v0
	v_mov_b32_e32 v92, v0
	v_mov_b32_e32 v93, v0
	v_mov_b32_e32 v98, v0
	v_mov_b32_e32 v99, v0
	v_mov_b32_e32 v100, v0
	v_mov_b32_e32 v101, v0
	v_mov_b32_e32 v106, v0
	v_mov_b32_e32 v107, v0
	v_mov_b32_e32 v108, v0
	v_mov_b32_e32 v109, v0
	v_mov_b32_e32 v114, v0
	v_mov_b32_e32 v115, v0
	v_mov_b32_e32 v116, v0
	v_mov_b32_e32 v117, v0
	v_mov_b32_e32 v78, v0
	v_mov_b32_e32 v79, v0
	v_mov_b32_e32 v80, v0
	v_mov_b32_e32 v81, v0
	v_mov_b32_e32 v86, v0
	v_mov_b32_e32 v87, v0
	v_mov_b32_e32 v88, v0
	v_mov_b32_e32 v89, v0
	v_mov_b32_e32 v94, v0
	v_mov_b32_e32 v95, v0
	v_mov_b32_e32 v96, v0
	v_mov_b32_e32 v97, v0
	v_mov_b32_e32 v102, v0
	v_mov_b32_e32 v103, v0
	v_mov_b32_e32 v104, v0
	v_mov_b32_e32 v105, v0
	v_mov_b32_e32 v110, v0
	v_mov_b32_e32 v111, v0
	v_mov_b32_e32 v112, v0
	v_mov_b32_e32 v113, v0
	v_mov_b32_e32 v118, v0
	v_mov_b32_e32 v119, v0
	v_mov_b32_e32 v120, v0
	v_mov_b32_e32 v121, v0
	v_mov_b32_e32 v122, v0
	v_mov_b32_e32 v123, v0
	v_mov_b32_e32 v124, v0
	v_mov_b32_e32 v125, v0
	v_mov_b32_e32 v126, v0
	v_mov_b32_e32 v127, v0
	v_mov_b32_e32 v128, v0
	v_mov_b32_e32 v129, v0
	v_add_u32_e32 v153, 0x10010, v154
	ds_read_b128 v[156:159], v153
	ds_read_b128 v[160:163], v153 offset:1024
	ds_read_b128 v[164:167], v153 offset:2048
	ds_read_b128 v[168:171], v153 offset:3072
.LBB0_187:
	s_add_u32 s20, s72, 0xfffc0080
	s_addc_u32 s21, s73, -1
	s_add_i32 s22, 16, 0x10000
	v_add_u32_e32 v153, s22, v154
	s_cmp_eq_u32 s19, 12
	s_cselect_b32 s71, s41, s21
	s_cselect_b32 s70, s78, s20
	s_cselect_b32 s67, s1, s18
	s_cselect_b32 s66, s16, s17
	v_lshl_add_u64 v[216:217], s[72:73], 0, v[148:149]
	s_add_i32 m0, s9, 0xc000
	ds_read_b128 v[172:175], v155
	ds_read_b128 v[188:191], v155 offset:1024
	ds_read_b128 v[192:195], v155 offset:2048
	ds_read_b128 v[196:199], v155 offset:3072
	ds_read_b128 v[200:203], v155 offset:4096
	ds_read_b128 v[204:207], v155 offset:5120
	ds_read_b128 v[208:211], v155 offset:6144
	ds_read_b128 v[212:215], v155 offset:7168
	global_load_lds_dwordx4 v[216:217], off
	v_lshl_add_u64 v[216:217], s[72:73], 0, v[150:151]
	s_add_i32 m0, s9, 0xe000
	s_nop 0
	global_load_lds_dwordx4 v[216:217], off
	s_waitcnt lgkmcnt(8)
	s_barrier
	s_waitcnt lgkmcnt(0)
	s_setprio 1
	s_waitcnt lgkmcnt(0)
	v_mfma_f32_16x16x32_bf16 v[126:129], v[156:159], v[172:175], v[126:129]
	v_mfma_f32_16x16x32_bf16 v[122:125], v[164:167], v[172:175], v[122:125]
	v_mfma_f32_16x16x32_bf16 v[118:121], v[156:159], v[192:195], v[118:121]
	v_mfma_f32_16x16x32_bf16 v[110:113], v[164:167], v[192:195], v[110:113]
	v_mfma_f32_16x16x32_bf16 v[102:105], v[156:159], v[200:203], v[102:105]
	v_mfma_f32_16x16x32_bf16 v[94:97], v[164:167], v[200:203], v[94:97]
	v_mfma_f32_16x16x32_bf16 v[86:89], v[156:159], v[208:211], v[86:89]
	v_mfma_f32_16x16x32_bf16 v[78:81], v[164:167], v[208:211], v[78:81]
	v_mfma_f32_16x16x32_bf16 v[126:129], v[160:163], v[188:191], v[126:129]
	v_mfma_f32_16x16x32_bf16 v[122:125], v[168:171], v[188:191], v[122:125]
	v_mfma_f32_16x16x32_bf16 v[118:121], v[160:163], v[196:199], v[118:121]
	v_mfma_f32_16x16x32_bf16 v[110:113], v[168:171], v[196:199], v[110:113]
	v_mfma_f32_16x16x32_bf16 v[102:105], v[160:163], v[204:207], v[102:105]
	v_mfma_f32_16x16x32_bf16 v[94:97], v[168:171], v[204:207], v[94:97]
	v_mfma_f32_16x16x32_bf16 v[86:89], v[160:163], v[212:215], v[86:89]
	v_mfma_f32_16x16x32_bf16 v[78:81], v[168:171], v[212:215], v[78:81]
	s_setprio 0
	s_barrier
; #define PG8_STAGE(bufoff, gbase, voff) do { _Pragma("unroll") for (int _i = 0; _i < 2; ++_i) \
;         __builtin_amdgcn_global_load_lds((const unsigned*)((const char*)(gbase) + (voff)[_i]), (LAS unsigned*)(lds + (bufoff) + ldsw + _i * 8192), 16, 0, 0); } while (0)
; #define PG8_LDA(dst, b, h) do { _Pragma("unroll") for (int m = 0; m < 4; ++m) _Pragma("unroll") for (int k = 0; k < 2; ++k) dst[m][k] = *(const LAS bf16x8*)(lds + PG8_SA(b, h) + aoff + m * 2048 + k * 1024); } while (0)
; #define PG8_LDB(dst, b, h) do { _Pragma("unroll") for (int n = 0; n < 2; ++n) _Pragma("unroll") for (int k = 0; k < 2; ++k) dst[n][k] = *(const LAS bf16x8*)(lds + PG8_SB(b, h) + boff + n * 2048 + k * 1024); } while (0)
; #define PG8_MMA(ai, bj, At, Bt) do { __builtin_amdgcn_s_setprio(1); _Pragma("unroll") for (int m = 0; m < 4; ++m) _Pragma("unroll") for (int n = 0; n < 2; ++n) _Pragma("unroll") for (int k = 0; k < 2; ++k) \
;         acc[ai][bj][m][n] = __builtin_amdgcn_mfma_f32_16x16x32_bf16(Bt[n][k], At[m][k], acc[ai][bj][m][n], 0, 0, 0); __builtin_amdgcn_s_setprio(0); } while (0)
; #define PG8_WAIT_V(n) asm volatile("s_waitcnt vmcnt(" #n ")" ::: "memory")
; #define PG8_WAIT_L(n) asm volatile("s_waitcnt lgkmcnt(" #n ")" ::: "memory")
; #define PG8_BAR __builtin_amdgcn_s_barrier()
; #define PG8_SCHED __builtin_amdgcn_sched_barrier(0)
; template <class Epi, class Sched>
; __device__ __forceinline__ void gemm_phase(LAS unsigned char* lds, const Gemm g, const Sched& S, const Epi& E) {
;     ...
;             PG8_LDB(B1, 0, 1); PG8_STAGE(PG8_SB(0, 0), b2, voffB);
;             PG8_BAR; PG8_WAIT_L(0); PG8_MMA(0, 1, At, B1); PG8_BAR;
;             PG8_LDA(At, 0, 1); PG8_STAGE(PG8_SA(0, 0), a2, voffA);
;             PG8_BAR; PG8_WAIT_L(0); PG8_MMA(1, 0, At, B0); PG8_BAR; PG8_SCHED;
;             PG8_STAGE(PG8_SB(0, 1), b2 + hstep, voffB);
;             PG8_WAIT_V(6); PG8_BAR; PG8_MMA(1, 1, At, B1); PG8_BAR;
;             PG8_LDB(B0, 1, 0); PG8_SCHED; PG8_LDA(At, 1, 0); PG8_STAGE(PG8_SA(0, 1), a2 + hstep, voffA);
;             PG8_WAIT_L(8); PG8_BAR; PG8_WAIT_L(0); PG8_MMA(0, 0, At, B0); PG8_BAR; PG8_SCHED;
	s_add_i32 s23, 16, 0x14000
	s_add_i32 s20, s22, s8
	v_add_u32_e32 v153, s23, v154
	v_lshl_add_u64 v[232:233], s[66:67], 0, v[144:145]
	s_mov_b32 m0, s20
	ds_read_b128 v[216:219], v153
	ds_read_b128 v[220:223], v153 offset:1024
	ds_read_b128 v[224:227], v153 offset:2048
	ds_read_b128 v[228:231], v153 offset:3072
	global_load_lds_dwordx4 v[232:233], off
	v_lshl_add_u64 v[234:235], s[66:67], 0, v[140:141]
	s_add_i32 m0, s20, 0x2000
	s_nop 0
	global_load_lds_dwordx4 v[234:235], off
	s_barrier
	s_waitcnt lgkmcnt(0)
	s_setprio 1
	s_waitcnt lgkmcnt(0)
	v_mfma_f32_16x16x32_bf16 v[114:117], v[216:219], v[172:175], v[114:117]
	v_mfma_f32_16x16x32_bf16 v[106:109], v[224:227], v[172:175], v[106:109]
	v_mfma_f32_16x16x32_bf16 v[98:101], v[216:219], v[192:195], v[98:101]
	v_mfma_f32_16x16x32_bf16 v[90:93], v[224:227], v[192:195], v[90:93]
	v_mfma_f32_16x16x32_bf16 v[82:85], v[216:219], v[200:203], v[82:85]
	v_mfma_f32_16x16x32_bf16 v[74:77], v[224:227], v[200:203], v[74:77]
	v_mfma_f32_16x16x32_bf16 v[70:73], v[216:219], v[208:211], v[70:73]
	v_mfma_f32_16x16x32_bf16 v[66:69], v[224:227], v[208:211], v[66:69]
	v_mfma_f32_16x16x32_bf16 v[114:117], v[220:223], v[188:191], v[114:117]
	v_mfma_f32_16x16x32_bf16 v[106:109], v[228:231], v[188:191], v[106:109]
	v_mfma_f32_16x16x32_bf16 v[98:101], v[220:223], v[196:199], v[98:101]
	v_mfma_f32_16x16x32_bf16 v[90:93], v[228:231], v[196:199], v[90:93]
	v_mfma_f32_16x16x32_bf16 v[82:85], v[220:223], v[204:207], v[82:85]
	v_mfma_f32_16x16x32_bf16 v[74:77], v[228:231], v[204:207], v[74:77]
	v_mfma_f32_16x16x32_bf16 v[70:73], v[220:223], v[212:215], v[70:73]
	v_mfma_f32_16x16x32_bf16 v[66:69], v[228:231], v[212:215], v[66:69]
	s_setprio 0
	s_mov_b32 m0, s9
	v_lshl_add_u64 v[236:237], s[70:71], 0, v[146:147]
	s_barrier
	ds_read_b128 v[172:175], v155 offset:16384
	ds_read_b128 v[188:191], v155 offset:17408
	ds_read_b128 v[192:195], v155 offset:18432
	ds_read_b128 v[196:199], v155 offset:19456
	ds_read_b128 v[200:203], v155 offset:20480
	ds_read_b128 v[204:207], v155 offset:21504
	ds_read_b128 v[208:211], v155 offset:22528
	ds_read_b128 v[212:215], v155 offset:23552
	global_load_lds_dwordx4 v[236:237], off
	v_lshl_add_u64 v[238:239], s[70:71], 0, v[142:143]
	s_mov_b32 m0, s10
	s_nop 0
	global_load_lds_dwordx4 v[238:239], off
	s_barrier
	s_waitcnt lgkmcnt(0)
	s_setprio 1
	s_waitcnt lgkmcnt(0)
	v_mfma_f32_16x16x32_bf16 v[62:65], v[156:159], v[172:175], v[62:65]
	v_mfma_f32_16x16x32_bf16 v[58:61], v[164:167], v[172:175], v[58:61]
	v_mfma_f32_16x16x32_bf16 v[54:57], v[156:159], v[192:195], v[54:57]
	v_mfma_f32_16x16x32_bf16 v[50:53], v[164:167], v[192:195], v[50:53]
	v_mfma_f32_16x16x32_bf16 v[38:41], v[156:159], v[200:203], v[38:41]
	v_mfma_f32_16x16x32_bf16 v[34:37], v[164:167], v[200:203], v[34:37]
	v_mfma_f32_16x16x32_bf16 v[22:25], v[156:159], v[208:211], v[22:25]
	v_mfma_f32_16x16x32_bf16 v[18:21], v[164:167], v[208:211], v[18:21]
	v_mfma_f32_16x16x32_bf16 v[62:65], v[160:163], v[188:191], v[62:65]
	v_mfma_f32_16x16x32_bf16 v[58:61], v[168:171], v[188:191], v[58:61]
	v_mfma_f32_16x16x32_bf16 v[54:57], v[160:163], v[196:199], v[54:57]
	v_mfma_f32_16x16x32_bf16 v[50:53], v[168:171], v[196:199], v[50:53]
	v_mfma_f32_16x16x32_bf16 v[38:41], v[160:163], v[204:207], v[38:41]
	v_mfma_f32_16x16x32_bf16 v[34:37], v[168:171], v[204:207], v[34:37]
	v_mfma_f32_16x16x32_bf16 v[22:25], v[160:163], v[212:215], v[22:25]
	v_mfma_f32_16x16x32_bf16 v[18:21], v[168:171], v[212:215], v[18:21]
	s_setprio 0
	s_barrier
	s_add_u32 s20, s66, 0x40000
	s_addc_u32 s21, s67, 0
	s_add_i32 s22, s23, s8
	v_lshl_add_u64 v[156:157], s[20:21], 0, v[144:145]
	s_mov_b32 m0, s22
	s_nop 0
	global_load_lds_dwordx4 v[156:157], off
	v_lshl_add_u64 v[156:157], s[20:21], 0, v[140:141]
	s_add_i32 m0, s22, 0x2000
	s_nop 0
	global_load_lds_dwordx4 v[156:157], off
	s_waitcnt vmcnt(6)
	s_barrier
	v_add_u32_e32 v153, 0x18010, v154
	ds_read_b128 v[156:159], v153
	ds_read_b128 v[160:163], v153 offset:1024
	ds_read_b128 v[164:167], v153 offset:2048
	ds_read_b128 v[168:171], v153 offset:3072
	s_setprio 1
	v_mfma_f32_16x16x32_bf16 v[46:49], v[216:219], v[172:175], v[46:49]
	v_mfma_f32_16x16x32_bf16 v[42:45], v[224:227], v[172:175], v[42:45]
	v_mfma_f32_16x16x32_bf16 v[30:33], v[216:219], v[192:195], v[30:33]
	v_mfma_f32_16x16x32_bf16 v[26:29], v[224:227], v[192:195], v[26:29]
	v_mfma_f32_16x16x32_bf16 v[14:17], v[216:219], v[200:203], v[14:17]
	v_mfma_f32_16x16x32_bf16 v[10:13], v[224:227], v[200:203], v[10:13]
	v_mfma_f32_16x16x32_bf16 v[4:7], v[216:219], v[208:211], v[4:7]
	v_mfma_f32_16x16x32_bf16 v[0:3], v[224:227], v[208:211], v[0:3]
	v_mfma_f32_16x16x32_bf16 v[46:49], v[220:223], v[188:191], v[46:49]
	v_mfma_f32_16x16x32_bf16 v[42:45], v[228:231], v[188:191], v[42:45]
	v_mfma_f32_16x16x32_bf16 v[30:33], v[220:223], v[196:199], v[30:33]
	v_mfma_f32_16x16x32_bf16 v[26:29], v[228:231], v[196:199], v[26:29]
	v_mfma_f32_16x16x32_bf16 v[14:17], v[220:223], v[204:207], v[14:17]
	v_mfma_f32_16x16x32_bf16 v[10:13], v[228:231], v[204:207], v[10:13]
	v_mfma_f32_16x16x32_bf16 v[4:7], v[220:223], v[212:215], v[4:7]
	v_mfma_f32_16x16x32_bf16 v[0:3], v[228:231], v[212:215], v[0:3]
	s_setprio 0
	s_add_i32 s22, 16, 0x18000
	v_add_u32_e32 v153, s22, v154
	s_barrier
	s_add_u32 s20, s70, 0x40000
	s_addc_u32 s21, s71, 0
	s_mov_b32 m0, s11
	v_lshl_add_u64 v[216:217], s[20:21], 0, v[146:147]
	ds_read_b128 v[172:175], v155 offset:32768
	ds_read_b128 v[188:191], v155 offset:33792
	ds_read_b128 v[192:195], v155 offset:34816
	ds_read_b128 v[196:199], v155 offset:35840
	ds_read_b128 v[200:203], v155 offset:36864
	ds_read_b128 v[204:207], v155 offset:37888
	ds_read_b128 v[208:211], v155 offset:38912
	ds_read_b128 v[212:215], v155 offset:39936
	global_load_lds_dwordx4 v[216:217], off
	v_lshl_add_u64 v[216:217], s[20:21], 0, v[142:143]
	s_mov_b32 m0, s12
	s_nop 0
	global_load_lds_dwordx4 v[216:217], off
	s_waitcnt lgkmcnt(8)
	s_barrier
; #define PG8_STAGE(bufoff, gbase, voff) do { _Pragma("unroll") for (int _i = 0; _i < 2; ++_i) \
;         __builtin_amdgcn_global_load_lds((const unsigned*)((const char*)(gbase) + (voff)[_i]), (LAS unsigned*)(lds + (bufoff) + ldsw + _i * 8192), 16, 0, 0); } while (0)
; #define PG8_LDA(dst, b, h) do { _Pragma("unroll") for (int m = 0; m < 4; ++m) _Pragma("unroll") for (int k = 0; k < 2; ++k) dst[m][k] = *(const LAS bf16x8*)(lds + PG8_SA(b, h) + aoff + m * 2048 + k * 1024); } while (0)
; #define PG8_LDB(dst, b, h) do { _Pragma("unroll") for (int n = 0; n < 2; ++n) _Pragma("unroll") for (int k = 0; k < 2; ++k) dst[n][k] = *(const LAS bf16x8*)(lds + PG8_SB(b, h) + boff + n * 2048 + k * 1024); } while (0)
; #define PG8_MMA(ai, bj, At, Bt) do { __builtin_amdgcn_s_setprio(1); _Pragma("unroll") for (int m = 0; m < 4; ++m) _Pragma("unroll") for (int n = 0; n < 2; ++n) _Pragma("unroll") for (int k = 0; k < 2; ++k) \
;         acc[ai][bj][m][n] = __builtin_amdgcn_mfma_f32_16x16x32_bf16(Bt[n][k], At[m][k], acc[ai][bj][m][n], 0, 0, 0); __builtin_amdgcn_s_setprio(0); } while (0)
; #define PG8_WAIT_L(n) asm volatile("s_waitcnt lgkmcnt(" #n ")" ::: "memory")
; #define PG8_BAR __builtin_amdgcn_s_barrier()
; #define PG8_SCHED __builtin_amdgcn_sched_barrier(0)
; template <class Epi, class Sched>
; __device__ __forceinline__ void gemm_phase(LAS unsigned char* lds, const Gemm g, const Sched& S, const Epi& E) {
;     ...
;             PG8_WAIT_L(8); PG8_BAR; PG8_WAIT_L(0); PG8_MMA(0, 0, At, B0); PG8_BAR; PG8_SCHED;
;             PG8_LDB(B1, 1, 1); PG8_STAGE(PG8_SB(1, 0), b3, voffB);
;             PG8_BAR; PG8_WAIT_L(0); PG8_MMA(0, 1, At, B1); PG8_BAR;
;             PG8_LDA(At, 1, 1); PG8_STAGE(PG8_SA(1, 0), a3, voffA);
;             PG8_BAR; PG8_WAIT_L(0); PG8_MMA(1, 0, At, B0); PG8_BAR; PG8_SCHED;
;             PG8_STAGE(PG8_SB(1, 1), b3 + hstep, voffB);
	s_waitcnt lgkmcnt(0)
	s_setprio 1
	s_waitcnt lgkmcnt(0)
	v_mfma_f32_16x16x32_bf16 v[126:129], v[156:159], v[172:175], v[126:129]
	v_mfma_f32_16x16x32_bf16 v[122:125], v[164:167], v[172:175], v[122:125]
	v_mfma_f32_16x16x32_bf16 v[118:121], v[156:159], v[192:195], v[118:121]
	v_mfma_f32_16x16x32_bf16 v[110:113], v[164:167], v[192:195], v[110:113]
	v_mfma_f32_16x16x32_bf16 v[102:105], v[156:159], v[200:203], v[102:105]
	v_mfma_f32_16x16x32_bf16 v[94:97], v[164:167], v[200:203], v[94:97]
	v_mfma_f32_16x16x32_bf16 v[86:89], v[156:159], v[208:211], v[86:89]
	v_mfma_f32_16x16x32_bf16 v[78:81], v[164:167], v[208:211], v[78:81]
	v_mfma_f32_16x16x32_bf16 v[126:129], v[160:163], v[188:191], v[126:129]
	v_mfma_f32_16x16x32_bf16 v[122:125], v[168:171], v[188:191], v[122:125]
	v_mfma_f32_16x16x32_bf16 v[118:121], v[160:163], v[196:199], v[118:121]
	v_mfma_f32_16x16x32_bf16 v[110:113], v[168:171], v[196:199], v[110:113]
	v_mfma_f32_16x16x32_bf16 v[102:105], v[160:163], v[204:207], v[102:105]
	v_mfma_f32_16x16x32_bf16 v[94:97], v[168:171], v[204:207], v[94:97]
	v_mfma_f32_16x16x32_bf16 v[86:89], v[160:163], v[212:215], v[86:89]
	v_mfma_f32_16x16x32_bf16 v[78:81], v[168:171], v[212:215], v[78:81]
	s_setprio 0
	s_barrier
	s_add_i32 s23, 16, 0x1c000
	s_add_i32 s20, s22, s8
	v_add_u32_e32 v153, s23, v154
	v_lshl_add_u64 v[232:233], v[232:233], 0, s[94:95]
	s_mov_b32 m0, s20
	ds_read_b128 v[216:219], v153
	ds_read_b128 v[220:223], v153 offset:1024
	ds_read_b128 v[224:227], v153 offset:2048
	ds_read_b128 v[228:231], v153 offset:3072
	global_load_lds_dwordx4 v[232:233], off
	v_lshl_add_u64 v[232:233], v[234:235], 0, s[94:95]
	s_add_i32 m0, s20, 0x2000
	s_nop 0
	global_load_lds_dwordx4 v[232:233], off
	s_barrier
	s_waitcnt lgkmcnt(0)
	s_setprio 1
	s_waitcnt lgkmcnt(0)
	v_mfma_f32_16x16x32_bf16 v[114:117], v[216:219], v[172:175], v[114:117]
	v_mfma_f32_16x16x32_bf16 v[106:109], v[224:227], v[172:175], v[106:109]
	v_mfma_f32_16x16x32_bf16 v[98:101], v[216:219], v[192:195], v[98:101]
	v_mfma_f32_16x16x32_bf16 v[90:93], v[224:227], v[192:195], v[90:93]
	v_mfma_f32_16x16x32_bf16 v[82:85], v[216:219], v[200:203], v[82:85]
	v_mfma_f32_16x16x32_bf16 v[74:77], v[224:227], v[200:203], v[74:77]
	v_mfma_f32_16x16x32_bf16 v[70:73], v[216:219], v[208:211], v[70:73]
	v_mfma_f32_16x16x32_bf16 v[66:69], v[224:227], v[208:211], v[66:69]
	v_mfma_f32_16x16x32_bf16 v[114:117], v[220:223], v[188:191], v[114:117]
	v_mfma_f32_16x16x32_bf16 v[106:109], v[228:231], v[188:191], v[106:109]
	v_mfma_f32_16x16x32_bf16 v[98:101], v[220:223], v[196:199], v[98:101]
	v_mfma_f32_16x16x32_bf16 v[90:93], v[228:231], v[196:199], v[90:93]
	v_mfma_f32_16x16x32_bf16 v[82:85], v[220:223], v[204:207], v[82:85]
	v_mfma_f32_16x16x32_bf16 v[74:77], v[228:231], v[204:207], v[74:77]
	v_mfma_f32_16x16x32_bf16 v[70:73], v[220:223], v[212:215], v[70:73]
	v_mfma_f32_16x16x32_bf16 v[66:69], v[228:231], v[212:215], v[66:69]
	s_setprio 0
	s_mov_b32 m0, s13
	v_lshl_add_u64 v[232:233], v[236:237], 0, s[94:95]
	s_barrier
	ds_read_b128 v[172:175], v155 offset:49152
	ds_read_b128 v[188:191], v155 offset:50176
	ds_read_b128 v[192:195], v155 offset:51200
	ds_read_b128 v[196:199], v155 offset:52224
	ds_read_b128 v[200:203], v155 offset:53248
	ds_read_b128 v[204:207], v155 offset:54272
	ds_read_b128 v[208:211], v155 offset:55296
	ds_read_b128 v[212:215], v155 offset:56320
	global_load_lds_dwordx4 v[232:233], off
	v_lshl_add_u64 v[232:233], v[238:239], 0, s[94:95]
	s_mov_b32 m0, s74
	s_nop 0
	global_load_lds_dwordx4 v[232:233], off
	s_barrier
	s_waitcnt lgkmcnt(0)
	s_setprio 1
	s_waitcnt lgkmcnt(0)
	v_mfma_f32_16x16x32_bf16 v[62:65], v[156:159], v[172:175], v[62:65]
	v_mfma_f32_16x16x32_bf16 v[58:61], v[164:167], v[172:175], v[58:61]
	v_mfma_f32_16x16x32_bf16 v[54:57], v[156:159], v[192:195], v[54:57]
	v_mfma_f32_16x16x32_bf16 v[50:53], v[164:167], v[192:195], v[50:53]
	v_mfma_f32_16x16x32_bf16 v[38:41], v[156:159], v[200:203], v[38:41]
	v_mfma_f32_16x16x32_bf16 v[34:37], v[164:167], v[200:203], v[34:37]
	v_mfma_f32_16x16x32_bf16 v[22:25], v[156:159], v[208:211], v[22:25]
	v_mfma_f32_16x16x32_bf16 v[18:21], v[164:167], v[208:211], v[18:21]
	v_mfma_f32_16x16x32_bf16 v[62:65], v[160:163], v[188:191], v[62:65]
	v_mfma_f32_16x16x32_bf16 v[58:61], v[168:171], v[188:191], v[58:61]
	v_mfma_f32_16x16x32_bf16 v[54:57], v[160:163], v[196:199], v[54:57]
	v_mfma_f32_16x16x32_bf16 v[50:53], v[168:171], v[196:199], v[50:53]
	v_mfma_f32_16x16x32_bf16 v[38:41], v[160:163], v[204:207], v[38:41]
	v_mfma_f32_16x16x32_bf16 v[34:37], v[168:171], v[204:207], v[34:37]
	v_mfma_f32_16x16x32_bf16 v[22:25], v[160:163], v[212:215], v[22:25]
	v_mfma_f32_16x16x32_bf16 v[18:21], v[168:171], v[212:215], v[18:21]
	s_setprio 0
	s_barrier
	s_add_u32 s20, s66, 0x40080
	s_addc_u32 s21, s67, 0
	s_add_i32 s22, s23, s8
	v_lshl_add_u64 v[156:157], s[20:21], 0, v[144:145]
	s_mov_b32 m0, s22
	s_nop 0
	global_load_lds_dwordx4 v[156:157], off
	v_lshl_add_u64 v[156:157], s[20:21], 0, v[140:141]
	s_add_i32 m0, s22, 0x2000
	s_nop 0
	global_load_lds_dwordx4 v[156:157], off
	s_waitcnt vmcnt(6)
	s_barrier
; __device__ __forceinline__ unsigned pk_bf16(float a, float b) { f32x2 v = {a, b}; bf2_t r = __builtin_convertvector(v, bf2_t); return __builtin_bit_cast(unsigned, r); }
; #define PG8_MMA(ai, bj, At, Bt) do { __builtin_amdgcn_s_setprio(1); _Pragma("unroll") for (int m = 0; m < 4; ++m) _Pragma("unroll") for (int n = 0; n < 2; ++n) _Pragma("unroll") for (int k = 0; k < 2; ++k) \
;         acc[ai][bj][m][n] = __builtin_amdgcn_mfma_f32_16x16x32_bf16(Bt[n][k], At[m][k], acc[ai][bj][m][n], 0, 0, 0); __builtin_amdgcn_s_setprio(0); } while (0)
; #define PG8_WAIT_V(n) asm volatile("s_waitcnt vmcnt(" #n ")" ::: "memory")
; #define PG8_BAR __builtin_amdgcn_s_barrier()
;     __device__ __forceinline__ void operator()(const f32x4 (&acc)[2][2][4][2], const Unit& u, int wr, int wc, int fr, int fq) const {
;         const int row0 = u.pm * BM + wr * 64 + fr; int colt = u.pn * BM; bf16_t* base = O;
;         if (split_cols) { const int t = colt / split_cols; base += (size_t)t * split_stride; colt -= t * split_cols; }
;         const int col0 = colt + wc * 32 + 8 * fq;
; #pragma unroll
;         for (int ai = 0; ai < 2; ++ai)
; #pragma unroll
;             for (int m = 0; m < 4; ++m) { const int row = row0 + ai * HALF + m * 16;
;                 bf16_t* rowp = slot_stride ? base + (size_t)(colt >> 7) * slot_stride + (size_t)row * 128 + wc * 32 + 8 * fq : base + (size_t)row * ldc + col0;
; #pragma unroll
;                 for (int bj = 0; bj < 2; ++bj) { const f32x4 v0 = acc[ai][bj][m][0], v1 = acc[ai][bj][m][1];
;                     u32x4 w; w.x = pk_bf16(v0[0], v0[1]); w.y = pk_bf16(v0[2], v0[3]); w.z = pk_bf16(v1[0], v1[1]); w.w = pk_bf16(v1[2], v1[3]);
;                     *(u32x4*)(rowp + (slot_stride ? (size_t)bj * slot_stride : (size_t)bj * HALF)) = w; } }
; template <class Epi, class Sched>
; __device__ __forceinline__ void gemm_phase(LAS unsigned char* lds, const Gemm g, const Sched& S, const Epi& E) {
;     ...
;             PG8_WAIT_V(6); PG8_BAR; PG8_MMA(1, 1, At, B1); PG8_BAR;
;         }
;         E(acc, cur, wr, wc, fr, fq); S.done(cur);
;         if (!has_next) break;
	v_add_u32_e32 v153, 0x10010, v154
	ds_read_b128 v[156:159], v153
	ds_read_b128 v[160:163], v153 offset:1024
	ds_read_b128 v[164:167], v153 offset:2048
	ds_read_b128 v[168:171], v153 offset:3072
	s_setprio 1
	v_mfma_f32_16x16x32_bf16 v[46:49], v[216:219], v[172:175], v[46:49]
	v_mfma_f32_16x16x32_bf16 v[42:45], v[224:227], v[172:175], v[42:45]
	v_mfma_f32_16x16x32_bf16 v[30:33], v[216:219], v[192:195], v[30:33]
	v_mfma_f32_16x16x32_bf16 v[26:29], v[224:227], v[192:195], v[26:29]
	v_mfma_f32_16x16x32_bf16 v[14:17], v[216:219], v[200:203], v[14:17]
	v_mfma_f32_16x16x32_bf16 v[10:13], v[224:227], v[200:203], v[10:13]
	v_mfma_f32_16x16x32_bf16 v[4:7], v[216:219], v[208:211], v[4:7]
	v_mfma_f32_16x16x32_bf16 v[0:3], v[224:227], v[208:211], v[0:3]
	v_mfma_f32_16x16x32_bf16 v[46:49], v[220:223], v[188:191], v[46:49]
	v_mfma_f32_16x16x32_bf16 v[42:45], v[228:231], v[188:191], v[42:45]
	v_mfma_f32_16x16x32_bf16 v[30:33], v[220:223], v[196:199], v[30:33]
	v_mfma_f32_16x16x32_bf16 v[26:29], v[228:231], v[196:199], v[26:29]
	v_mfma_f32_16x16x32_bf16 v[14:17], v[220:223], v[204:207], v[14:17]
	v_mfma_f32_16x16x32_bf16 v[10:13], v[228:231], v[204:207], v[10:13]
	v_mfma_f32_16x16x32_bf16 v[4:7], v[220:223], v[212:215], v[4:7]
	v_mfma_f32_16x16x32_bf16 v[0:3], v[228:231], v[212:215], v[0:3]
	s_setprio 0
	s_add_i32 s19, s19, 2
	s_add_u32 s72, s72, 0x100
	s_addc_u32 s73, s73, 0
	s_add_u32 s17, s17, 0x100
	s_addc_u32 s18, s18, 0
	s_cmp_gt_u32 s19, 13
	s_barrier
	s_cbranch_scc0 .LBB0_187
	s_waitcnt lgkmcnt(0)
	v_lshl_add_u32 v156, s75, 8, v9
	s_lshl_b32 s1, s15, 1
	s_mul_i32 s15, s15, 0x1100000
	s_mul_hi_i32 s1, s1, 0x880000
	s_add_u32 s66, s82, s15
	v_ashrrev_i32_e32 v157, 31, v156
	s_addc_u32 s67, s83, s1
	v_lshlrev_b64 v[158:159], 8, v[156:157]
	v_lshl_add_u64 v[158:159], s[66:67], 0, v[158:159]
	v_lshl_add_u64 v[158:159], v[158:159], 0, s[2:3]
	v_mov_b32_e32 v153, v8
	v_lshl_add_u64 v[158:159], v[158:159], 0, v[152:153]
	v_cvt_pk_bf16_f32 v114, v114, v115
	v_cvt_pk_bf16_f32 v115, v116, v117
	v_cvt_pk_bf16_f32 v116, v106, v107
	v_add_co_u32_e32 v106, vcc, s87, v158
	v_cvt_pk_bf16_f32 v117, v108, v109
	s_nop 0
	v_addc_co_u32_e32 v107, vcc, 0, v159, vcc
	global_store_dwordx4 v[106:107], v[114:117], off
	v_or_b32_e32 v106, 16, v156
	v_ashrrev_i32_e32 v107, 31, v106
	v_lshlrev_b64 v[106:107], 8, v[106:107]
	v_lshl_add_u64 v[106:107], s[66:67], 0, v[106:107]
	v_lshl_add_u64 v[106:107], v[106:107], 0, s[2:3]
	v_lshl_add_u64 v[114:115], v[106:107], 0, v[152:153]
	v_cvt_pk_bf16_f32 v98, v98, v99
	v_cvt_pk_bf16_f32 v99, v100, v101
	v_cvt_pk_bf16_f32 v100, v90, v91
	v_add_co_u32_e32 v90, vcc, s87, v114
	v_cvt_pk_bf16_f32 v101, v92, v93
	s_nop 0
	v_addc_co_u32_e32 v91, vcc, 0, v115, vcc
	global_store_dwordx4 v[90:91], v[98:101], off
	v_or_b32_e32 v90, 32, v156
	v_ashrrev_i32_e32 v91, 31, v90
	v_lshlrev_b64 v[90:91], 8, v[90:91]
	v_lshl_add_u64 v[90:91], s[66:67], 0, v[90:91]
	v_lshl_add_u64 v[90:91], v[90:91], 0, s[2:3]
	v_lshl_add_u64 v[98:99], v[90:91], 0, v[152:153]
	v_cvt_pk_bf16_f32 v82, v82, v83
	v_cvt_pk_bf16_f32 v83, v84, v85
	v_cvt_pk_bf16_f32 v84, v74, v75
	v_add_co_u32_e32 v74, vcc, s87, v98
	v_cvt_pk_bf16_f32 v85, v76, v77
	s_nop 0
	v_addc_co_u32_e32 v75, vcc, 0, v99, vcc
	global_store_dwordx4 v[74:75], v[82:85], off
	v_or_b32_e32 v74, 48, v156
	v_ashrrev_i32_e32 v75, 31, v74
	v_lshlrev_b64 v[74:75], 8, v[74:75]
	v_lshl_add_u64 v[74:75], s[66:67], 0, v[74:75]
	v_lshl_add_u64 v[74:75], v[74:75], 0, s[2:3]
	v_lshl_add_u64 v[82:83], v[74:75], 0, v[152:153]
	v_cvt_pk_bf16_f32 v70, v70, v71
	v_cvt_pk_bf16_f32 v71, v72, v73
	v_cvt_pk_bf16_f32 v72, v66, v67
	v_add_co_u32_e32 v66, vcc, s87, v82
	s_mov_b32 s1, 0x9000
	s_nop 0
	v_addc_co_u32_e32 v67, vcc, 0, v83, vcc
	v_cvt_pk_bf16_f32 v62, v62, v63
	v_cvt_pk_bf16_f32 v63, v64, v65
	v_cvt_pk_bf16_f32 v64, v58, v59
	v_add_co_u32_e32 v58, vcc, s1, v158
	s_mov_b32 s1, 0x889000
	s_nop 0
	v_addc_co_u32_e32 v59, vcc, 0, v159, vcc
	v_cvt_pk_bf16_f32 v65, v60, v61
	v_add_co_u32_e32 v60, vcc, s1, v158
	v_cvt_pk_bf16_f32 v30, v30, v31
	s_nop 0
	v_addc_co_u32_e32 v61, vcc, 0, v159, vcc
	v_cvt_pk_bf16_f32 v31, v32, v33
	v_cvt_pk_bf16_f32 v32, v26, v27
	v_cvt_pk_bf16_f32 v33, v28, v29
	s_mov_b32 s1, 0xb000
	global_store_dwordx4 v[60:61], v[30:33], off
	v_cvt_pk_bf16_f32 v14, v14, v15
	v_cvt_pk_bf16_f32 v15, v16, v17
	v_add_co_u32_e32 v30, vcc, s1, v158
	s_mov_b32 s1, 0x88a000
	s_nop 0
	v_addc_co_u32_e32 v31, vcc, 0, v159, vcc
	v_cvt_pk_bf16_f32 v16, v10, v11
	v_add_co_u32_e32 v10, vcc, s1, v158
	v_cvt_pk_bf16_f32 v4, v4, v5
	s_nop 0
	v_addc_co_u32_e32 v11, vcc, 0, v159, vcc
	v_cvt_pk_bf16_f32 v5, v6, v7
	v_cvt_pk_bf16_f32 v6, v0, v1
	v_add_co_u32_e32 v0, vcc, 0x88b000, v158
	v_cvt_pk_bf16_f32 v17, v12, v13
	s_nop 0
	v_addc_co_u32_e32 v1, vcc, 0, v159, vcc
	v_cvt_pk_bf16_f32 v126, v126, v127
	v_cvt_pk_bf16_f32 v127, v128, v129
	v_cvt_pk_bf16_f32 v128, v122, v123
	v_cvt_pk_bf16_f32 v129, v124, v125
	v_cvt_pk_bf16_f32 v106, v118, v119
	v_cvt_pk_bf16_f32 v107, v120, v121
	v_cvt_pk_bf16_f32 v108, v110, v111
	v_cvt_pk_bf16_f32 v109, v112, v113
	v_cvt_pk_bf16_f32 v90, v102, v103
	v_cvt_pk_bf16_f32 v91, v104, v105
	v_cvt_pk_bf16_f32 v92, v94, v95
	v_cvt_pk_bf16_f32 v93, v96, v97
	v_cvt_pk_bf16_f32 v74, v86, v87
	v_cvt_pk_bf16_f32 v75, v88, v89
	v_cvt_pk_bf16_f32 v76, v78, v79
	v_cvt_pk_bf16_f32 v77, v80, v81
	v_cvt_pk_bf16_f32 v73, v68, v69
	v_cvt_pk_bf16_f32 v46, v46, v47
	v_cvt_pk_bf16_f32 v47, v48, v49
	v_cvt_pk_bf16_f32 v48, v42, v43
	v_cvt_pk_bf16_f32 v49, v44, v45
	v_cvt_pk_bf16_f32 v42, v54, v55
	v_cvt_pk_bf16_f32 v43, v56, v57
	v_cvt_pk_bf16_f32 v44, v50, v51
	v_cvt_pk_bf16_f32 v45, v52, v53
	v_cvt_pk_bf16_f32 v26, v38, v39
	v_cvt_pk_bf16_f32 v27, v40, v41
	v_cvt_pk_bf16_f32 v28, v34, v35
	v_cvt_pk_bf16_f32 v29, v36, v37
	global_store_dwordx4 v[10:11], v[14:17], off
	v_cvt_pk_bf16_f32 v10, v22, v23
	v_cvt_pk_bf16_f32 v11, v24, v25
	v_cvt_pk_bf16_f32 v12, v18, v19
	v_cvt_pk_bf16_f32 v13, v20, v21
	v_cvt_pk_bf16_f32 v7, v2, v3
	s_and_b64 vcc, exec, s[38:39]
	s_mov_b32 s15, s0
	s_mov_b32 s75, s40
	s_mov_b64 s[66:67], s[88:89]
	s_mov_b64 s[70:71], s[42:43]
	global_store_dwordx4 v[158:159], v[126:129], off
	global_store_dwordx4 v[114:115], v[106:109], off
	global_store_dwordx4 v[98:99], v[90:93], off
	global_store_dwordx4 v[82:83], v[74:77], off
	global_store_dwordx4 v[66:67], v[70:73], off
	global_store_dwordx4 v[58:59], v[62:65], off offset:-4096
	global_store_dwordx4 v[60:61], v[46:49], off offset:-4096
	global_store_dwordx4 v[58:59], v[42:45], off
	global_store_dwordx4 v[30:31], v[26:29], off offset:-4096
	global_store_dwordx4 v[30:31], v[10:13], off
	global_store_dwordx4 v[0:1], v[4:7], off
	s_cbranch_vccz .LBB0_184
	s_waitcnt vmcnt(0)
	v_readlane_b32 s14, v244, 49
	v_readlane_b32 s16, v244, 51
	v_readlane_b32 s70, v244, 55
	s_cmpk_gt_u32 s5, 0xff
	v_readlane_b32 s15, v244, 50
	v_readlane_b32 s17, v244, 52
	v_readlane_b32 s71, v244, 56
	s_cbranch_scc1 .LBB0_191
	s_barrier

; #define PG8_STAGE(bufoff, gbase, voff) do { _Pragma("unroll") for (int _i = 0; _i < 2; ++_i) \
;         __builtin_amdgcn_global_load_lds((const unsigned*)((const char*)(gbase) + (voff)[_i]), (LAS unsigned*)(lds + (bufoff) + ldsw + _i * 8192), 16, 0, 0); } while (0)
; #define PG8_LDA(dst, b, h) do { _Pragma("unroll") for (int m = 0; m < 4; ++m) _Pragma("unroll") for (int k = 0; k < 2; ++k) dst[m][k] = *(const LAS bf16x8*)(lds + PG8_SA(b, h) + aoff + m * 2048 + k * 1024); } while (0)
; #define PG8_LDB(dst, b, h) do { _Pragma("unroll") for (int n = 0; n < 2; ++n) _Pragma("unroll") for (int k = 0; k < 2; ++k) dst[n][k] = *(const LAS bf16x8*)(lds + PG8_SB(b, h) + boff + n * 2048 + k * 1024); } while (0)
; template <class Epi, class Sched>
; __device__ __forceinline__ void gemm_phase(LAS unsigned char* lds, const Gemm g, const Sched& S, const Epi& E) {
;     ...
;                 for (int n = 0; n < 2; ++n) acc[a][b][m][n] = (f32x4){0.f, 0.f, 0.f, 0.f};
;     bf16x8 At[4][2], B0[2][2], B1[2][2];
;     const char* cA = (const char*)g.A + (size_t)cur.pm * tstep; const char* cB = (const char*)g.Bt + (size_t)cur.pn * tstep;
;     S.a_ready(cur);
;     PG8_STAGE(PG8_SB(0, 0), cB, voffB); PG8_STAGE(PG8_SA(0, 0), cA, voffA); PG8_STAGE(PG8_SB(0, 1), cB + hstep, voffB); PG8_STAGE(PG8_SA(0, 1), cA + hstep, voffA);
;     if (wr == 1) PG8_BAR;
;     PG8_WAIT_V(4); PG8_BAR;
;     PG8_STAGE(PG8_SB(1, 0), cB + kstep, voffB); PG8_STAGE(PG8_SA(1, 0), cA + kstep, voffA); PG8_STAGE(PG8_SB(1, 1), cB + hstep + kstep, voffB);
;     PG8_WAIT_V(6); PG8_BAR;
;     for (;;) {
;         const bool has_next = S.next(ui + 1, nxt);
;         const char* nA = has_next ? (const char*)g.A + (size_t)nxt.pm * tstep : cA; const char* nB = has_next ? (const char*)g.Bt + (size_t)nxt.pn * tstep : cB;
;         for (int t = 0; t < nt; t += 2) {
;             const bool last = (t == nt - 2);
;             const char* a1 = cA + (size_t)(t + 1) * kstep;
;             const char* a2 = last ? nA : cA + (size_t)(t + 2) * kstep; const char* b2 = last ? nB : cB + (size_t)(t + 2) * kstep;
;             const char* a3 = a2 + kstep; const char* b3 = b2 + kstep;
;             if (last && has_next) S.a_ready(nxt);
;             PG8_LDB(B0, 0, 0); PG8_SCHED; PG8_LDA(At, 0, 0); PG8_STAGE(PG8_SA(1, 1), a1 + hstep, voffA);
;             PG8_WAIT_L(8); PG8_BAR; PG8_WAIT_L(0); PG8_MMA(0, 0, At, B0); PG8_BAR; PG8_SCHED;
.LBB0_514:
	s_ashr_i32 s89, s88, 31
	s_lshl_b64 s[16:17], s[88:89], 19
	v_mov_b64_e32 v[0:1], s[2:3]
	s_add_u32 s78, s76, s16
	v_cmp_lt_i64_e32 vcc, s[66:67], v[0:1]
	s_addc_u32 s79, s77, s17
	s_and_b64 s[16:17], vcc, exec
	s_cselect_b32 s89, s79, s73
	s_cselect_b32 s16, s78, s72
	s_ashr_i32 s43, s42, 31
	s_lshl_b64 s[18:19], s[42:43], 19
	s_add_u32 s70, s7, s18
	s_addc_u32 s71, s8, s19
	s_and_b64 s[18:19], vcc, exec
	s_cselect_b32 s17, s71, s75
	s_cselect_b32 s43, s70, s74
	s_add_u32 vcc_lo, s72, 0x40080
	s_addc_u32 vcc_hi, s73, 0
	s_add_u32 s74, s74, 0x100
	v_mov_b32_e32 v0, 0
	s_addc_u32 s18, s75, 0
	s_mov_b32 s19, -2
	v_mov_b32_e32 v1, v0
	v_mov_b32_e32 v2, v0
	v_mov_b32_e32 v3, v0
	v_mov_b32_e32 v4, v0
	v_mov_b32_e32 v5, v0
	v_mov_b32_e32 v6, v0
	v_mov_b32_e32 v7, v0
	v_mov_b32_e32 v10, v0
	v_mov_b32_e32 v11, v0
	v_mov_b32_e32 v12, v0
	v_mov_b32_e32 v13, v0
	v_mov_b32_e32 v14, v0
	v_mov_b32_e32 v15, v0
	v_mov_b32_e32 v16, v0
	v_mov_b32_e32 v17, v0
	v_mov_b32_e32 v26, v0
	v_mov_b32_e32 v27, v0
	v_mov_b32_e32 v28, v0
	v_mov_b32_e32 v29, v0
	v_mov_b32_e32 v30, v0
	v_mov_b32_e32 v31, v0
	v_mov_b32_e32 v32, v0
	v_mov_b32_e32 v33, v0
	v_mov_b32_e32 v42, v0
	v_mov_b32_e32 v43, v0
	v_mov_b32_e32 v44, v0
	v_mov_b32_e32 v45, v0
	v_mov_b32_e32 v46, v0
	v_mov_b32_e32 v47, v0
	v_mov_b32_e32 v48, v0
	v_mov_b32_e32 v49, v0
	v_mov_b32_e32 v18, v0
	v_mov_b32_e32 v19, v0
	v_mov_b32_e32 v20, v0
	v_mov_b32_e32 v21, v0
	v_mov_b32_e32 v22, v0
	v_mov_b32_e32 v23, v0
	v_mov_b32_e32 v24, v0
	v_mov_b32_e32 v25, v0
	v_mov_b32_e32 v34, v0
	v_mov_b32_e32 v35, v0
	v_mov_b32_e32 v36, v0
	v_mov_b32_e32 v37, v0
	v_mov_b32_e32 v38, v0
	v_mov_b32_e32 v39, v0
	v_mov_b32_e32 v40, v0
	v_mov_b32_e32 v41, v0
	v_mov_b32_e32 v50, v0
	v_mov_b32_e32 v51, v0
	v_mov_b32_e32 v52, v0
	v_mov_b32_e32 v53, v0
	v_mov_b32_e32 v54, v0
	v_mov_b32_e32 v55, v0
	v_mov_b32_e32 v56, v0
	v_mov_b32_e32 v57, v0
	v_mov_b32_e32 v58, v0
	v_mov_b32_e32 v59, v0
	v_mov_b32_e32 v60, v0
	v_mov_b32_e32 v61, v0
	v_mov_b32_e32 v62, v0
	v_mov_b32_e32 v63, v0
	v_mov_b32_e32 v64, v0
	v_mov_b32_e32 v65, v0
	v_mov_b32_e32 v66, v0
	v_mov_b32_e32 v67, v0
	v_mov_b32_e32 v68, v0
	v_mov_b32_e32 v69, v0
	v_mov_b32_e32 v70, v0
	v_mov_b32_e32 v71, v0
	v_mov_b32_e32 v72, v0
	v_mov_b32_e32 v73, v0
	v_mov_b32_e32 v74, v0
	v_mov_b32_e32 v75, v0
	v_mov_b32_e32 v76, v0
	v_mov_b32_e32 v77, v0
	v_mov_b32_e32 v78, v0
	v_mov_b32_e32 v79, v0
	v_mov_b32_e32 v80, v0
	v_mov_b32_e32 v81, v0
	v_mov_b32_e32 v90, v0
	v_mov_b32_e32 v91, v0
	v_mov_b32_e32 v92, v0
	v_mov_b32_e32 v93, v0
	v_mov_b32_e32 v94, v0
	v_mov_b32_e32 v95, v0
	v_mov_b32_e32 v96, v0
	v_mov_b32_e32 v97, v0
	v_mov_b32_e32 v106, v0
	v_mov_b32_e32 v107, v0
	v_mov_b32_e32 v108, v0
	v_mov_b32_e32 v109, v0
	v_mov_b32_e32 v110, v0
	v_mov_b32_e32 v111, v0
	v_mov_b32_e32 v112, v0
	v_mov_b32_e32 v113, v0
	v_mov_b32_e32 v82, v0
	v_mov_b32_e32 v83, v0
	v_mov_b32_e32 v84, v0
	v_mov_b32_e32 v85, v0
	v_mov_b32_e32 v86, v0
	v_mov_b32_e32 v87, v0
	v_mov_b32_e32 v88, v0
	v_mov_b32_e32 v89, v0
	v_mov_b32_e32 v98, v0
	v_mov_b32_e32 v99, v0
	v_mov_b32_e32 v100, v0
	v_mov_b32_e32 v101, v0
	v_mov_b32_e32 v102, v0
	v_mov_b32_e32 v103, v0
	v_mov_b32_e32 v104, v0
	v_mov_b32_e32 v105, v0
	v_mov_b32_e32 v114, v0
	v_mov_b32_e32 v115, v0
	v_mov_b32_e32 v116, v0
	v_mov_b32_e32 v117, v0
	v_mov_b32_e32 v118, v0
	v_mov_b32_e32 v119, v0
	v_mov_b32_e32 v120, v0
	v_mov_b32_e32 v121, v0
	v_mov_b32_e32 v122, v0
	v_mov_b32_e32 v123, v0
	v_mov_b32_e32 v124, v0
	v_mov_b32_e32 v125, v0
	v_mov_b32_e32 v126, v0
	v_mov_b32_e32 v127, v0
	v_mov_b32_e32 v128, v0
	v_mov_b32_e32 v129, v0
	v_add_u32_e32 v155, 0x10010, v152
	ds_read_b128 v[156:159], v155
	ds_read_b128 v[160:163], v155 offset:1024
	ds_read_b128 v[164:167], v155 offset:2048
	ds_read_b128 v[168:171], v155 offset:3072
.LBB0_515:
	s_add_u32 s20, vcc_lo, 0xfffc0080
	s_addc_u32 s21, vcc_hi, -1
	s_add_i32 s22, 16, 0x10000
	v_add_u32_e32 v155, s22, v152
	s_cmp_eq_u32 s19, 12
	s_cselect_b32 s73, s89, s21
	s_cselect_b32 s72, s16, s20
	s_cselect_b32 s67, s17, s18
	s_cselect_b32 s66, s43, s74
	v_lshl_add_u64 v[216:217], vcc, 0, v[148:149]
	s_add_i32 m0, s1, 0xc000
	ds_read_b128 v[172:175], v154
	ds_read_b128 v[188:191], v154 offset:1024
	ds_read_b128 v[192:195], v154 offset:2048
	ds_read_b128 v[196:199], v154 offset:3072
	ds_read_b128 v[200:203], v154 offset:4096
	ds_read_b128 v[204:207], v154 offset:5120
	ds_read_b128 v[208:211], v154 offset:6144
	ds_read_b128 v[212:215], v154 offset:7168
	global_load_lds_dwordx4 v[216:217], off
	v_lshl_add_u64 v[216:217], vcc, 0, v[150:151]
	s_add_i32 m0, s1, 0xe000
	s_nop 0
	global_load_lds_dwordx4 v[216:217], off
	s_waitcnt lgkmcnt(8)
	s_barrier
	s_waitcnt lgkmcnt(0)
	s_setprio 1
	s_waitcnt lgkmcnt(0)
	v_mfma_f32_16x16x32_bf16 v[126:129], v[156:159], v[172:175], v[126:129]
	v_mfma_f32_16x16x32_bf16 v[122:125], v[164:167], v[172:175], v[122:125]
	v_mfma_f32_16x16x32_bf16 v[118:121], v[156:159], v[192:195], v[118:121]
	v_mfma_f32_16x16x32_bf16 v[114:117], v[164:167], v[192:195], v[114:117]
	v_mfma_f32_16x16x32_bf16 v[102:105], v[156:159], v[200:203], v[102:105]
	v_mfma_f32_16x16x32_bf16 v[98:101], v[164:167], v[200:203], v[98:101]
	v_mfma_f32_16x16x32_bf16 v[86:89], v[156:159], v[208:211], v[86:89]
	v_mfma_f32_16x16x32_bf16 v[82:85], v[164:167], v[208:211], v[82:85]
	v_mfma_f32_16x16x32_bf16 v[126:129], v[160:163], v[188:191], v[126:129]
	v_mfma_f32_16x16x32_bf16 v[122:125], v[168:171], v[188:191], v[122:125]
	v_mfma_f32_16x16x32_bf16 v[118:121], v[160:163], v[196:199], v[118:121]
	v_mfma_f32_16x16x32_bf16 v[114:117], v[168:171], v[196:199], v[114:117]
	v_mfma_f32_16x16x32_bf16 v[102:105], v[160:163], v[204:207], v[102:105]
	v_mfma_f32_16x16x32_bf16 v[98:101], v[168:171], v[204:207], v[98:101]
	v_mfma_f32_16x16x32_bf16 v[86:89], v[160:163], v[212:215], v[86:89]
	v_mfma_f32_16x16x32_bf16 v[82:85], v[168:171], v[212:215], v[82:85]
	s_setprio 0
	s_barrier
; #define PG8_STAGE(bufoff, gbase, voff) do { _Pragma("unroll") for (int _i = 0; _i < 2; ++_i) \
;         __builtin_amdgcn_global_load_lds((const unsigned*)((const char*)(gbase) + (voff)[_i]), (LAS unsigned*)(lds + (bufoff) + ldsw + _i * 8192), 16, 0, 0); } while (0)
; #define PG8_LDA(dst, b, h) do { _Pragma("unroll") for (int m = 0; m < 4; ++m) _Pragma("unroll") for (int k = 0; k < 2; ++k) dst[m][k] = *(const LAS bf16x8*)(lds + PG8_SA(b, h) + aoff + m * 2048 + k * 1024); } while (0)
; #define PG8_LDB(dst, b, h) do { _Pragma("unroll") for (int n = 0; n < 2; ++n) _Pragma("unroll") for (int k = 0; k < 2; ++k) dst[n][k] = *(const LAS bf16x8*)(lds + PG8_SB(b, h) + boff + n * 2048 + k * 1024); } while (0)
; #define PG8_MMA(ai, bj, At, Bt) do { __builtin_amdgcn_s_setprio(1); _Pragma("unroll") for (int m = 0; m < 4; ++m) _Pragma("unroll") for (int n = 0; n < 2; ++n) _Pragma("unroll") for (int k = 0; k < 2; ++k) \
;         acc[ai][bj][m][n] = __builtin_amdgcn_mfma_f32_16x16x32_bf16(Bt[n][k], At[m][k], acc[ai][bj][m][n], 0, 0, 0); __builtin_amdgcn_s_setprio(0); } while (0)
; #define PG8_WAIT_V(n) asm volatile("s_waitcnt vmcnt(" #n ")" ::: "memory")
; #define PG8_WAIT_L(n) asm volatile("s_waitcnt lgkmcnt(" #n ")" ::: "memory")
; #define PG8_BAR __builtin_amdgcn_s_barrier()
; #define PG8_SCHED __builtin_amdgcn_sched_barrier(0)
; template <class Epi, class Sched>
; __device__ __forceinline__ void gemm_phase(LAS unsigned char* lds, const Gemm g, const Sched& S, const Epi& E) {
;     ...
;             PG8_LDB(B1, 0, 1); PG8_STAGE(PG8_SB(0, 0), b2, voffB);
;             PG8_BAR; PG8_WAIT_L(0); PG8_MMA(0, 1, At, B1); PG8_BAR;
;             PG8_LDA(At, 0, 1); PG8_STAGE(PG8_SA(0, 0), a2, voffA);
;             PG8_BAR; PG8_WAIT_L(0); PG8_MMA(1, 0, At, B0); PG8_BAR; PG8_SCHED;
;             PG8_STAGE(PG8_SB(0, 1), b2 + hstep, voffB);
;             PG8_WAIT_V(6); PG8_BAR; PG8_MMA(1, 1, At, B1); PG8_BAR;
;             PG8_LDB(B0, 1, 0); PG8_SCHED; PG8_LDA(At, 1, 0); PG8_STAGE(PG8_SA(0, 1), a2 + hstep, voffA);
;             PG8_WAIT_L(8); PG8_BAR; PG8_WAIT_L(0); PG8_MMA(0, 0, At, B0); PG8_BAR; PG8_SCHED;
	s_add_i32 s23, 16, 0x14000
	s_add_i32 s20, s22, s9
	v_add_u32_e32 v155, s23, v152
	v_lshl_add_u64 v[232:233], s[66:67], 0, v[144:145]
	s_mov_b32 m0, s20
	ds_read_b128 v[216:219], v155
	ds_read_b128 v[220:223], v155 offset:1024
	ds_read_b128 v[224:227], v155 offset:2048
	ds_read_b128 v[228:231], v155 offset:3072
	global_load_lds_dwordx4 v[232:233], off
	v_lshl_add_u64 v[234:235], s[66:67], 0, v[140:141]
	s_add_i32 m0, s20, 0x2000
	s_nop 0
	global_load_lds_dwordx4 v[234:235], off
	s_barrier
	s_waitcnt lgkmcnt(0)
	s_setprio 1
	s_waitcnt lgkmcnt(0)
	v_mfma_f32_16x16x32_bf16 v[110:113], v[216:219], v[172:175], v[110:113]
	v_mfma_f32_16x16x32_bf16 v[106:109], v[224:227], v[172:175], v[106:109]
	v_mfma_f32_16x16x32_bf16 v[94:97], v[216:219], v[192:195], v[94:97]
	v_mfma_f32_16x16x32_bf16 v[90:93], v[224:227], v[192:195], v[90:93]
	v_mfma_f32_16x16x32_bf16 v[78:81], v[216:219], v[200:203], v[78:81]
	v_mfma_f32_16x16x32_bf16 v[74:77], v[224:227], v[200:203], v[74:77]
	v_mfma_f32_16x16x32_bf16 v[70:73], v[216:219], v[208:211], v[70:73]
	v_mfma_f32_16x16x32_bf16 v[66:69], v[224:227], v[208:211], v[66:69]
	v_mfma_f32_16x16x32_bf16 v[110:113], v[220:223], v[188:191], v[110:113]
	v_mfma_f32_16x16x32_bf16 v[106:109], v[228:231], v[188:191], v[106:109]
	v_mfma_f32_16x16x32_bf16 v[94:97], v[220:223], v[196:199], v[94:97]
	v_mfma_f32_16x16x32_bf16 v[90:93], v[228:231], v[196:199], v[90:93]
	v_mfma_f32_16x16x32_bf16 v[78:81], v[220:223], v[204:207], v[78:81]
	v_mfma_f32_16x16x32_bf16 v[74:77], v[228:231], v[204:207], v[74:77]
	v_mfma_f32_16x16x32_bf16 v[70:73], v[220:223], v[212:215], v[70:73]
	v_mfma_f32_16x16x32_bf16 v[66:69], v[228:231], v[212:215], v[66:69]
	s_setprio 0
	s_mov_b32 m0, s1
	v_lshl_add_u64 v[236:237], s[72:73], 0, v[146:147]
	s_barrier
	ds_read_b128 v[172:175], v154 offset:16384
	ds_read_b128 v[188:191], v154 offset:17408
	ds_read_b128 v[192:195], v154 offset:18432
	ds_read_b128 v[196:199], v154 offset:19456
	ds_read_b128 v[200:203], v154 offset:20480
	ds_read_b128 v[204:207], v154 offset:21504
	ds_read_b128 v[208:211], v154 offset:22528
	ds_read_b128 v[212:215], v154 offset:23552
	global_load_lds_dwordx4 v[236:237], off
	v_lshl_add_u64 v[238:239], s[72:73], 0, v[142:143]
	s_mov_b32 m0, s11
	s_nop 0
	global_load_lds_dwordx4 v[238:239], off
	s_barrier
	s_waitcnt lgkmcnt(0)
	s_setprio 1
	s_waitcnt lgkmcnt(0)
	v_mfma_f32_16x16x32_bf16 v[62:65], v[156:159], v[172:175], v[62:65]
	v_mfma_f32_16x16x32_bf16 v[58:61], v[164:167], v[172:175], v[58:61]
	v_mfma_f32_16x16x32_bf16 v[54:57], v[156:159], v[192:195], v[54:57]
	v_mfma_f32_16x16x32_bf16 v[50:53], v[164:167], v[192:195], v[50:53]
	v_mfma_f32_16x16x32_bf16 v[38:41], v[156:159], v[200:203], v[38:41]
	v_mfma_f32_16x16x32_bf16 v[34:37], v[164:167], v[200:203], v[34:37]
	v_mfma_f32_16x16x32_bf16 v[22:25], v[156:159], v[208:211], v[22:25]
	v_mfma_f32_16x16x32_bf16 v[18:21], v[164:167], v[208:211], v[18:21]
	v_mfma_f32_16x16x32_bf16 v[62:65], v[160:163], v[188:191], v[62:65]
	v_mfma_f32_16x16x32_bf16 v[58:61], v[168:171], v[188:191], v[58:61]
	v_mfma_f32_16x16x32_bf16 v[54:57], v[160:163], v[196:199], v[54:57]
	v_mfma_f32_16x16x32_bf16 v[50:53], v[168:171], v[196:199], v[50:53]
	v_mfma_f32_16x16x32_bf16 v[38:41], v[160:163], v[204:207], v[38:41]
	v_mfma_f32_16x16x32_bf16 v[34:37], v[168:171], v[204:207], v[34:37]
	v_mfma_f32_16x16x32_bf16 v[22:25], v[160:163], v[212:215], v[22:25]
	v_mfma_f32_16x16x32_bf16 v[18:21], v[168:171], v[212:215], v[18:21]
	s_setprio 0
	s_barrier
	s_add_u32 s20, s66, 0x40000
	s_addc_u32 s21, s67, 0
	s_add_i32 s22, s23, s9
	v_lshl_add_u64 v[156:157], s[20:21], 0, v[144:145]
	s_mov_b32 m0, s22
	s_nop 0
	global_load_lds_dwordx4 v[156:157], off
	v_lshl_add_u64 v[156:157], s[20:21], 0, v[140:141]
	s_add_i32 m0, s22, 0x2000
	s_nop 0
	global_load_lds_dwordx4 v[156:157], off
	s_waitcnt vmcnt(6)
	s_barrier
	v_add_u32_e32 v155, 0x18010, v152
	ds_read_b128 v[156:159], v155
	ds_read_b128 v[160:163], v155 offset:1024
	ds_read_b128 v[164:167], v155 offset:2048
	ds_read_b128 v[168:171], v155 offset:3072
	s_setprio 1
	v_mfma_f32_16x16x32_bf16 v[46:49], v[216:219], v[172:175], v[46:49]
	v_mfma_f32_16x16x32_bf16 v[42:45], v[224:227], v[172:175], v[42:45]
	v_mfma_f32_16x16x32_bf16 v[30:33], v[216:219], v[192:195], v[30:33]
	v_mfma_f32_16x16x32_bf16 v[26:29], v[224:227], v[192:195], v[26:29]
	v_mfma_f32_16x16x32_bf16 v[14:17], v[216:219], v[200:203], v[14:17]
	v_mfma_f32_16x16x32_bf16 v[10:13], v[224:227], v[200:203], v[10:13]
	v_mfma_f32_16x16x32_bf16 v[4:7], v[216:219], v[208:211], v[4:7]
	v_mfma_f32_16x16x32_bf16 v[0:3], v[224:227], v[208:211], v[0:3]
	v_mfma_f32_16x16x32_bf16 v[46:49], v[220:223], v[188:191], v[46:49]
	v_mfma_f32_16x16x32_bf16 v[42:45], v[228:231], v[188:191], v[42:45]
	v_mfma_f32_16x16x32_bf16 v[30:33], v[220:223], v[196:199], v[30:33]
	v_mfma_f32_16x16x32_bf16 v[26:29], v[228:231], v[196:199], v[26:29]
	v_mfma_f32_16x16x32_bf16 v[14:17], v[220:223], v[204:207], v[14:17]
	v_mfma_f32_16x16x32_bf16 v[10:13], v[228:231], v[204:207], v[10:13]
	v_mfma_f32_16x16x32_bf16 v[4:7], v[220:223], v[212:215], v[4:7]
	v_mfma_f32_16x16x32_bf16 v[0:3], v[228:231], v[212:215], v[0:3]
	s_setprio 0
	s_add_i32 s22, 16, 0x18000
	v_add_u32_e32 v155, s22, v152
	s_barrier
	s_add_u32 s20, s72, 0x40000
	s_addc_u32 s21, s73, 0
	s_mov_b32 m0, s41
	v_lshl_add_u64 v[216:217], s[20:21], 0, v[146:147]
	ds_read_b128 v[172:175], v154 offset:32768
	ds_read_b128 v[188:191], v154 offset:33792
	ds_read_b128 v[192:195], v154 offset:34816
	ds_read_b128 v[196:199], v154 offset:35840
	ds_read_b128 v[200:203], v154 offset:36864
	ds_read_b128 v[204:207], v154 offset:37888
	ds_read_b128 v[208:211], v154 offset:38912
	ds_read_b128 v[212:215], v154 offset:39936
	global_load_lds_dwordx4 v[216:217], off
	v_lshl_add_u64 v[216:217], s[20:21], 0, v[142:143]
	s_mov_b32 m0, s12
	s_nop 0
	global_load_lds_dwordx4 v[216:217], off
	s_waitcnt lgkmcnt(8)
	s_barrier
; #define PG8_STAGE(bufoff, gbase, voff) do { _Pragma("unroll") for (int _i = 0; _i < 2; ++_i) \
;         __builtin_amdgcn_global_load_lds((const unsigned*)((const char*)(gbase) + (voff)[_i]), (LAS unsigned*)(lds + (bufoff) + ldsw + _i * 8192), 16, 0, 0); } while (0)
; #define PG8_LDA(dst, b, h) do { _Pragma("unroll") for (int m = 0; m < 4; ++m) _Pragma("unroll") for (int k = 0; k < 2; ++k) dst[m][k] = *(const LAS bf16x8*)(lds + PG8_SA(b, h) + aoff + m * 2048 + k * 1024); } while (0)
; #define PG8_LDB(dst, b, h) do { _Pragma("unroll") for (int n = 0; n < 2; ++n) _Pragma("unroll") for (int k = 0; k < 2; ++k) dst[n][k] = *(const LAS bf16x8*)(lds + PG8_SB(b, h) + boff + n * 2048 + k * 1024); } while (0)
; #define PG8_MMA(ai, bj, At, Bt) do { __builtin_amdgcn_s_setprio(1); _Pragma("unroll") for (int m = 0; m < 4; ++m) _Pragma("unroll") for (int n = 0; n < 2; ++n) _Pragma("unroll") for (int k = 0; k < 2; ++k) \
;         acc[ai][bj][m][n] = __builtin_amdgcn_mfma_f32_16x16x32_bf16(Bt[n][k], At[m][k], acc[ai][bj][m][n], 0, 0, 0); __builtin_amdgcn_s_setprio(0); } while (0)
; #define PG8_WAIT_L(n) asm volatile("s_waitcnt lgkmcnt(" #n ")" ::: "memory")
; #define PG8_BAR __builtin_amdgcn_s_barrier()
; #define PG8_SCHED __builtin_amdgcn_sched_barrier(0)
; template <class Epi, class Sched>
; __device__ __forceinline__ void gemm_phase(LAS unsigned char* lds, const Gemm g, const Sched& S, const Epi& E) {
;     ...
;             PG8_WAIT_L(8); PG8_BAR; PG8_WAIT_L(0); PG8_MMA(0, 0, At, B0); PG8_BAR; PG8_SCHED;
;             PG8_LDB(B1, 1, 1); PG8_STAGE(PG8_SB(1, 0), b3, voffB);
;             PG8_BAR; PG8_WAIT_L(0); PG8_MMA(0, 1, At, B1); PG8_BAR;
;             PG8_LDA(At, 1, 1); PG8_STAGE(PG8_SA(1, 0), a3, voffA);
;             PG8_BAR; PG8_WAIT_L(0); PG8_MMA(1, 0, At, B0); PG8_BAR; PG8_SCHED;
;             PG8_STAGE(PG8_SB(1, 1), b3 + hstep, voffB);
	s_waitcnt lgkmcnt(0)
	s_setprio 1
	s_waitcnt lgkmcnt(0)
	v_mfma_f32_16x16x32_bf16 v[126:129], v[156:159], v[172:175], v[126:129]
	v_mfma_f32_16x16x32_bf16 v[122:125], v[164:167], v[172:175], v[122:125]
	v_mfma_f32_16x16x32_bf16 v[118:121], v[156:159], v[192:195], v[118:121]
	v_mfma_f32_16x16x32_bf16 v[114:117], v[164:167], v[192:195], v[114:117]
	v_mfma_f32_16x16x32_bf16 v[102:105], v[156:159], v[200:203], v[102:105]
	v_mfma_f32_16x16x32_bf16 v[98:101], v[164:167], v[200:203], v[98:101]
	v_mfma_f32_16x16x32_bf16 v[86:89], v[156:159], v[208:211], v[86:89]
	v_mfma_f32_16x16x32_bf16 v[82:85], v[164:167], v[208:211], v[82:85]
	v_mfma_f32_16x16x32_bf16 v[126:129], v[160:163], v[188:191], v[126:129]
	v_mfma_f32_16x16x32_bf16 v[122:125], v[168:171], v[188:191], v[122:125]
	v_mfma_f32_16x16x32_bf16 v[118:121], v[160:163], v[196:199], v[118:121]
	v_mfma_f32_16x16x32_bf16 v[114:117], v[168:171], v[196:199], v[114:117]
	v_mfma_f32_16x16x32_bf16 v[102:105], v[160:163], v[204:207], v[102:105]
	v_mfma_f32_16x16x32_bf16 v[98:101], v[168:171], v[204:207], v[98:101]
	v_mfma_f32_16x16x32_bf16 v[86:89], v[160:163], v[212:215], v[86:89]
	v_mfma_f32_16x16x32_bf16 v[82:85], v[168:171], v[212:215], v[82:85]
	s_setprio 0
	s_barrier
	s_add_i32 s23, 16, 0x1c000
	s_add_i32 s20, s22, s9
	v_add_u32_e32 v155, s23, v152
	v_lshl_add_u64 v[232:233], v[232:233], 0, s[94:95]
	s_mov_b32 m0, s20
	ds_read_b128 v[216:219], v155
	ds_read_b128 v[220:223], v155 offset:1024
	ds_read_b128 v[224:227], v155 offset:2048
	ds_read_b128 v[228:231], v155 offset:3072
	global_load_lds_dwordx4 v[232:233], off
	v_lshl_add_u64 v[232:233], v[234:235], 0, s[94:95]
	s_add_i32 m0, s20, 0x2000
	s_nop 0
	global_load_lds_dwordx4 v[232:233], off
	s_barrier
	s_waitcnt lgkmcnt(0)
	s_setprio 1
	s_waitcnt lgkmcnt(0)
	v_mfma_f32_16x16x32_bf16 v[110:113], v[216:219], v[172:175], v[110:113]
	v_mfma_f32_16x16x32_bf16 v[106:109], v[224:227], v[172:175], v[106:109]
	v_mfma_f32_16x16x32_bf16 v[94:97], v[216:219], v[192:195], v[94:97]
	v_mfma_f32_16x16x32_bf16 v[90:93], v[224:227], v[192:195], v[90:93]
	v_mfma_f32_16x16x32_bf16 v[78:81], v[216:219], v[200:203], v[78:81]
	v_mfma_f32_16x16x32_bf16 v[74:77], v[224:227], v[200:203], v[74:77]
	v_mfma_f32_16x16x32_bf16 v[70:73], v[216:219], v[208:211], v[70:73]
	v_mfma_f32_16x16x32_bf16 v[66:69], v[224:227], v[208:211], v[66:69]
	v_mfma_f32_16x16x32_bf16 v[110:113], v[220:223], v[188:191], v[110:113]
	v_mfma_f32_16x16x32_bf16 v[106:109], v[228:231], v[188:191], v[106:109]
	v_mfma_f32_16x16x32_bf16 v[94:97], v[220:223], v[196:199], v[94:97]
	v_mfma_f32_16x16x32_bf16 v[90:93], v[228:231], v[196:199], v[90:93]
	v_mfma_f32_16x16x32_bf16 v[78:81], v[220:223], v[204:207], v[78:81]
	v_mfma_f32_16x16x32_bf16 v[74:77], v[228:231], v[204:207], v[74:77]
	v_mfma_f32_16x16x32_bf16 v[70:73], v[220:223], v[212:215], v[70:73]
	v_mfma_f32_16x16x32_bf16 v[66:69], v[228:231], v[212:215], v[66:69]
	s_setprio 0
	s_mov_b32 m0, s13
	v_lshl_add_u64 v[232:233], v[236:237], 0, s[94:95]
	s_barrier
	ds_read_b128 v[172:175], v154 offset:49152
	ds_read_b128 v[188:191], v154 offset:50176
	ds_read_b128 v[192:195], v154 offset:51200
	ds_read_b128 v[196:199], v154 offset:52224
	ds_read_b128 v[200:203], v154 offset:53248
	ds_read_b128 v[204:207], v154 offset:54272
	ds_read_b128 v[208:211], v154 offset:55296
	ds_read_b128 v[212:215], v154 offset:56320
	global_load_lds_dwordx4 v[232:233], off
	v_lshl_add_u64 v[232:233], v[238:239], 0, s[94:95]
	s_mov_b32 m0, s14
	s_nop 0
	global_load_lds_dwordx4 v[232:233], off
	s_barrier
	s_waitcnt lgkmcnt(0)
	s_setprio 1
	s_waitcnt lgkmcnt(0)
	v_mfma_f32_16x16x32_bf16 v[62:65], v[156:159], v[172:175], v[62:65]
	v_mfma_f32_16x16x32_bf16 v[58:61], v[164:167], v[172:175], v[58:61]
	v_mfma_f32_16x16x32_bf16 v[54:57], v[156:159], v[192:195], v[54:57]
	v_mfma_f32_16x16x32_bf16 v[50:53], v[164:167], v[192:195], v[50:53]
	v_mfma_f32_16x16x32_bf16 v[38:41], v[156:159], v[200:203], v[38:41]
	v_mfma_f32_16x16x32_bf16 v[34:37], v[164:167], v[200:203], v[34:37]
	v_mfma_f32_16x16x32_bf16 v[22:25], v[156:159], v[208:211], v[22:25]
	v_mfma_f32_16x16x32_bf16 v[18:21], v[164:167], v[208:211], v[18:21]
	v_mfma_f32_16x16x32_bf16 v[62:65], v[160:163], v[188:191], v[62:65]
	v_mfma_f32_16x16x32_bf16 v[58:61], v[168:171], v[188:191], v[58:61]
	v_mfma_f32_16x16x32_bf16 v[54:57], v[160:163], v[196:199], v[54:57]
	v_mfma_f32_16x16x32_bf16 v[50:53], v[168:171], v[196:199], v[50:53]
	v_mfma_f32_16x16x32_bf16 v[38:41], v[160:163], v[204:207], v[38:41]
	v_mfma_f32_16x16x32_bf16 v[34:37], v[168:171], v[204:207], v[34:37]
	v_mfma_f32_16x16x32_bf16 v[22:25], v[160:163], v[212:215], v[22:25]
	v_mfma_f32_16x16x32_bf16 v[18:21], v[168:171], v[212:215], v[18:21]
	s_setprio 0
	s_barrier
	s_add_u32 s20, s66, 0x40080
	s_addc_u32 s21, s67, 0
	s_add_i32 s22, s23, s9
	v_lshl_add_u64 v[156:157], s[20:21], 0, v[144:145]
	s_mov_b32 m0, s22
	s_nop 0
	global_load_lds_dwordx4 v[156:157], off
	v_lshl_add_u64 v[156:157], s[20:21], 0, v[140:141]
	s_add_i32 m0, s22, 0x2000
	s_nop 0
	global_load_lds_dwordx4 v[156:157], off
	s_waitcnt vmcnt(6)
	s_barrier
; __device__ __forceinline__ unsigned pk_bf16(float a, float b) { f32x2 v = {a, b}; bf2_t r = __builtin_convertvector(v, bf2_t); return __builtin_bit_cast(unsigned, r); }
; #define PG8_MMA(ai, bj, At, Bt) do { __builtin_amdgcn_s_setprio(1); _Pragma("unroll") for (int m = 0; m < 4; ++m) _Pragma("unroll") for (int n = 0; n < 2; ++n) _Pragma("unroll") for (int k = 0; k < 2; ++k) \
;         acc[ai][bj][m][n] = __builtin_amdgcn_mfma_f32_16x16x32_bf16(Bt[n][k], At[m][k], acc[ai][bj][m][n], 0, 0, 0); __builtin_amdgcn_s_setprio(0); } while (0)
; #define PG8_WAIT_V(n) asm volatile("s_waitcnt vmcnt(" #n ")" ::: "memory")
; #define PG8_BAR __builtin_amdgcn_s_barrier()
;     __device__ __forceinline__ void operator()(const f32x4 (&acc)[2][2][4][2], const Unit& u, int wr, int wc, int fr, int fq) const {
;         const int row0 = u.pm * BM + wr * 64 + fr; int colt = u.pn * BM; bf16_t* base = O;
;         if (split_cols) { const int t = colt / split_cols; base += (size_t)t * split_stride; colt -= t * split_cols; }
;         const int col0 = colt + wc * 32 + 8 * fq;
; #pragma unroll
;         for (int ai = 0; ai < 2; ++ai)
; #pragma unroll
;             for (int m = 0; m < 4; ++m) { const int row = row0 + ai * HALF + m * 16;
;                 bf16_t* rowp = slot_stride ? base + (size_t)(colt >> 7) * slot_stride + (size_t)row * 128 + wc * 32 + 8 * fq : base + (size_t)row * ldc + col0;
; #pragma unroll
;                 for (int bj = 0; bj < 2; ++bj) { const f32x4 v0 = acc[ai][bj][m][0], v1 = acc[ai][bj][m][1];
;                     u32x4 w; w.x = pk_bf16(v0[0], v0[1]); w.y = pk_bf16(v0[2], v0[3]); w.z = pk_bf16(v1[0], v1[1]); w.w = pk_bf16(v1[2], v1[3]);
;                     *(u32x4*)(rowp + (slot_stride ? (size_t)bj * slot_stride : (size_t)bj * HALF)) = w; } }
; template <class Epi, class Sched>
; __device__ __forceinline__ void gemm_phase(LAS unsigned char* lds, const Gemm g, const Sched& S, const Epi& E) {
;     ...
;             PG8_WAIT_V(6); PG8_BAR; PG8_MMA(1, 1, At, B1); PG8_BAR;
;         }
;         E(acc, cur, wr, wc, fr, fq); S.done(cur);
;         if (!has_next) break;
	v_add_u32_e32 v155, 0x10010, v152
	ds_read_b128 v[156:159], v155
	ds_read_b128 v[160:163], v155 offset:1024
	ds_read_b128 v[164:167], v155 offset:2048
	ds_read_b128 v[168:171], v155 offset:3072
	s_setprio 1
	v_mfma_f32_16x16x32_bf16 v[46:49], v[216:219], v[172:175], v[46:49]
	v_mfma_f32_16x16x32_bf16 v[42:45], v[224:227], v[172:175], v[42:45]
	v_mfma_f32_16x16x32_bf16 v[30:33], v[216:219], v[192:195], v[30:33]
	v_mfma_f32_16x16x32_bf16 v[26:29], v[224:227], v[192:195], v[26:29]
	v_mfma_f32_16x16x32_bf16 v[14:17], v[216:219], v[200:203], v[14:17]
	v_mfma_f32_16x16x32_bf16 v[10:13], v[224:227], v[200:203], v[10:13]
	v_mfma_f32_16x16x32_bf16 v[4:7], v[216:219], v[208:211], v[4:7]
	v_mfma_f32_16x16x32_bf16 v[0:3], v[224:227], v[208:211], v[0:3]
	v_mfma_f32_16x16x32_bf16 v[46:49], v[220:223], v[188:191], v[46:49]
	v_mfma_f32_16x16x32_bf16 v[42:45], v[228:231], v[188:191], v[42:45]
	v_mfma_f32_16x16x32_bf16 v[30:33], v[220:223], v[196:199], v[30:33]
	v_mfma_f32_16x16x32_bf16 v[26:29], v[228:231], v[196:199], v[26:29]
	v_mfma_f32_16x16x32_bf16 v[14:17], v[220:223], v[204:207], v[14:17]
	v_mfma_f32_16x16x32_bf16 v[10:13], v[228:231], v[204:207], v[10:13]
	v_mfma_f32_16x16x32_bf16 v[4:7], v[220:223], v[212:215], v[4:7]
	v_mfma_f32_16x16x32_bf16 v[0:3], v[228:231], v[212:215], v[0:3]
	s_setprio 0
	s_add_i32 s19, s19, 2
	s_add_u32 vcc_lo, vcc_lo, 0x100
	s_addc_u32 vcc_hi, vcc_hi, 0
	s_add_u32 s74, s74, 0x100
	s_addc_u32 s18, s18, 0
	s_cmp_gt_u32 s19, 13
	s_barrier
	s_cbranch_scc0 .LBB0_515
	s_waitcnt lgkmcnt(0)
	v_lshl_add_u32 v156, s40, 8, v9
	v_lshl_or_b32 v158, s0, 8, v153
	v_ashrrev_i32_e32 v159, 31, v158
	v_ashrrev_i32_e32 v157, 31, v156
	v_lshl_add_u64 v[158:159], v[158:159], 1, s[82:83]
	v_lshlrev_b64 v[160:161], 11, v[156:157]
	v_lshl_add_u64 v[160:161], v[158:159], 0, v[160:161]
	s_mov_b32 s0, 0x40000
	s_mov_b64 s[16:17], 0x40000
	v_cvt_pk_bf16_f32 v62, v62, v63
	v_cvt_pk_bf16_f32 v63, v64, v65
	v_cvt_pk_bf16_f32 v64, v58, v59
	v_add_co_u32_e32 v58, vcc, s0, v160
	v_cvt_pk_bf16_f32 v70, v70, v71
	v_cvt_pk_bf16_f32 v71, v72, v73
	v_cvt_pk_bf16_f32 v72, v66, v67
	v_lshl_add_u64 v[66:67], v[160:161], 0, s[16:17]
	v_addc_co_u32_e32 v59, vcc, 0, v161, vcc
	v_cvt_pk_bf16_f32 v46, v46, v47
	v_cvt_pk_bf16_f32 v47, v48, v49
	v_cvt_pk_bf16_f32 v48, v42, v43
	v_cvt_pk_bf16_f32 v49, v44, v45
	s_mov_b32 s0, 0x48000
	global_store_dwordx4 v[66:67], v[46:49], off offset:256
	s_mov_b64 s[16:17], 0x48000
	v_cvt_pk_bf16_f32 v110, v110, v111
	v_add_co_u32_e32 v48, vcc, s0, v160
	v_cvt_pk_bf16_f32 v111, v112, v113
	v_cvt_pk_bf16_f32 v112, v106, v107
	v_or_b32_e32 v106, 16, v156
	v_lshl_add_u64 v[46:47], v[160:161], 0, s[16:17]
	v_addc_co_u32_e32 v49, vcc, 0, v161, vcc
	v_cvt_pk_bf16_f32 v30, v30, v31
	v_cvt_pk_bf16_f32 v31, v32, v33
	v_cvt_pk_bf16_f32 v32, v26, v27
	v_cvt_pk_bf16_f32 v33, v28, v29
	s_mov_b32 s0, 0x50000
	v_ashrrev_i32_e32 v107, 31, v106
	v_cvt_pk_bf16_f32 v94, v94, v95
	v_cvt_pk_bf16_f32 v95, v96, v97
	v_cvt_pk_bf16_f32 v96, v90, v91
	v_or_b32_e32 v90, 32, v156
	global_store_dwordx4 v[46:47], v[30:33], off offset:256
	s_mov_b64 s[16:17], 0x50000
	v_cvt_pk_bf16_f32 v113, v108, v109
	v_add_co_u32_e32 v32, vcc, s0, v160
	v_lshlrev_b64 v[106:107], 11, v[106:107]
	v_ashrrev_i32_e32 v91, 31, v90
	v_cvt_pk_bf16_f32 v78, v78, v79
	v_cvt_pk_bf16_f32 v79, v80, v81
	v_cvt_pk_bf16_f32 v80, v74, v75
	v_or_b32_e32 v74, 48, v156
	v_lshl_add_u64 v[30:31], v[160:161], 0, s[16:17]
	v_addc_co_u32_e32 v33, vcc, 0, v161, vcc
	v_cvt_pk_bf16_f32 v14, v14, v15
	v_cvt_pk_bf16_f32 v15, v16, v17
	v_cvt_pk_bf16_f32 v16, v10, v11
	v_cvt_pk_bf16_f32 v17, v12, v13
	s_mov_b32 s0, 0x58000
	global_store_dwordx4 v[160:161], v[110:113], off offset:256
	v_cvt_pk_bf16_f32 v97, v92, v93
	v_lshlrev_b64 v[90:91], 11, v[90:91]
	v_lshl_add_u64 v[110:111], v[158:159], 0, v[106:107]
	v_ashrrev_i32_e32 v75, 31, v74
	global_store_dwordx4 v[30:31], v[14:17], off offset:256
	global_store_dwordx4 v[110:111], v[94:97], off offset:256
	v_cvt_pk_bf16_f32 v81, v76, v77
	v_add_co_u32_e32 v16, vcc, s0, v160
	v_lshl_add_u64 v[94:95], v[158:159], 0, v[90:91]
	v_lshlrev_b64 v[74:75], 11, v[74:75]
	s_mov_b64 s[16:17], 0x58000
	v_addc_co_u32_e32 v17, vcc, 0, v161, vcc
	v_cvt_pk_bf16_f32 v126, v126, v127
	v_cvt_pk_bf16_f32 v127, v128, v129
	v_cvt_pk_bf16_f32 v128, v122, v123
	v_cvt_pk_bf16_f32 v129, v124, v125
	v_cvt_pk_bf16_f32 v106, v118, v119
	v_cvt_pk_bf16_f32 v107, v120, v121
	v_cvt_pk_bf16_f32 v108, v114, v115
	v_cvt_pk_bf16_f32 v109, v116, v117
	v_cvt_pk_bf16_f32 v90, v102, v103
	v_cvt_pk_bf16_f32 v91, v104, v105
	v_cvt_pk_bf16_f32 v92, v98, v99
	v_cvt_pk_bf16_f32 v93, v100, v101
	global_store_dwordx4 v[94:95], v[78:81], off offset:256
	v_cvt_pk_bf16_f32 v76, v82, v83
	v_cvt_pk_bf16_f32 v77, v84, v85
	v_lshl_add_u64 v[78:79], v[158:159], 0, v[74:75]
	v_cvt_pk_bf16_f32 v74, v86, v87
	v_cvt_pk_bf16_f32 v75, v88, v89
	v_cvt_pk_bf16_f32 v73, v68, v69
	v_cvt_pk_bf16_f32 v65, v60, v61
	v_cvt_pk_bf16_f32 v42, v54, v55
	v_cvt_pk_bf16_f32 v43, v56, v57
	v_cvt_pk_bf16_f32 v44, v50, v51
	v_cvt_pk_bf16_f32 v45, v52, v53
	v_cvt_pk_bf16_f32 v26, v38, v39
	v_cvt_pk_bf16_f32 v27, v40, v41
	v_cvt_pk_bf16_f32 v28, v34, v35
	v_cvt_pk_bf16_f32 v29, v36, v37
	v_lshl_add_u64 v[14:15], v[160:161], 0, s[16:17]
	v_cvt_pk_bf16_f32 v10, v22, v23
	v_cvt_pk_bf16_f32 v11, v24, v25
	v_cvt_pk_bf16_f32 v12, v18, v19
	v_cvt_pk_bf16_f32 v13, v20, v21
	v_cvt_pk_bf16_f32 v4, v4, v5
	v_cvt_pk_bf16_f32 v5, v6, v7
	v_cvt_pk_bf16_f32 v6, v0, v1
	v_cvt_pk_bf16_f32 v7, v2, v3
	s_and_b64 vcc, exec, s[38:39]
	s_mov_b32 s0, s42
	s_mov_b32 s40, s88
	s_mov_b64 s[74:75], s[70:71]
	s_mov_b64 s[72:73], s[78:79]
	global_store_dwordx4 v[160:161], v[126:129], off
	global_store_dwordx4 v[110:111], v[106:109], off
	global_store_dwordx4 v[94:95], v[90:93], off
	global_store_dwordx4 v[78:79], v[74:77], off
	global_store_dwordx4 v[78:79], v[70:73], off offset:256
	global_store_dwordx4 v[58:59], v[62:65], off
	global_store_dwordx4 v[48:49], v[42:45], off
	global_store_dwordx4 v[32:33], v[26:29], off
	global_store_dwordx4 v[16:17], v[10:13], off
	global_store_dwordx4 v[14:15], v[4:7], off offset:256
	s_cbranch_vccz .LBB0_512
	s_waitcnt vmcnt(0)
	s_cmpk_gt_u32 s6, 0xff
	s_cbranch_scc1 .LBB0_519
	s_barrier

; #define PG8_STAGE(bufoff, gbase, voff) do { _Pragma("unroll") for (int _i = 0; _i < 2; ++_i) \
;         __builtin_amdgcn_global_load_lds((const unsigned*)((const char*)(gbase) + (voff)[_i]), (LAS unsigned*)(lds + (bufoff) + ldsw + _i * 8192), 16, 0, 0); } while (0)
; #define PG8_LDA(dst, b, h) do { _Pragma("unroll") for (int m = 0; m < 4; ++m) _Pragma("unroll") for (int k = 0; k < 2; ++k) dst[m][k] = *(const LAS bf16x8*)(lds + PG8_SA(b, h) + aoff + m * 2048 + k * 1024); } while (0)
; #define PG8_LDB(dst, b, h) do { _Pragma("unroll") for (int n = 0; n < 2; ++n) _Pragma("unroll") for (int k = 0; k < 2; ++k) dst[n][k] = *(const LAS bf16x8*)(lds + PG8_SB(b, h) + boff + n * 2048 + k * 1024); } while (0)
; template <class Epi, class Sched>
; __device__ __forceinline__ void gemm_phase(LAS unsigned char* lds, const Gemm g, const Sched& S, const Epi& E) {
;     ...
;                 for (int n = 0; n < 2; ++n) acc[a][b][m][n] = (f32x4){0.f, 0.f, 0.f, 0.f};
;     bf16x8 At[4][2], B0[2][2], B1[2][2];
;     const char* cA = (const char*)g.A + (size_t)cur.pm * tstep; const char* cB = (const char*)g.Bt + (size_t)cur.pn * tstep;
;     S.a_ready(cur);
;     PG8_STAGE(PG8_SB(0, 0), cB, voffB); PG8_STAGE(PG8_SA(0, 0), cA, voffA); PG8_STAGE(PG8_SB(0, 1), cB + hstep, voffB); PG8_STAGE(PG8_SA(0, 1), cA + hstep, voffA);
;     if (wr == 1) PG8_BAR;
;     PG8_WAIT_V(4); PG8_BAR;
;     PG8_STAGE(PG8_SB(1, 0), cB + kstep, voffB); PG8_STAGE(PG8_SA(1, 0), cA + kstep, voffA); PG8_STAGE(PG8_SB(1, 1), cB + hstep + kstep, voffB);
;     PG8_WAIT_V(6); PG8_BAR;
;     for (;;) {
;         const bool has_next = S.next(ui + 1, nxt);
;         const char* nA = has_next ? (const char*)g.A + (size_t)nxt.pm * tstep : cA; const char* nB = has_next ? (const char*)g.Bt + (size_t)nxt.pn * tstep : cB;
;         for (int t = 0; t < nt; t += 2) {
;             const bool last = (t == nt - 2);
;             const char* a1 = cA + (size_t)(t + 1) * kstep;
;             const char* a2 = last ? nA : cA + (size_t)(t + 2) * kstep; const char* b2 = last ? nB : cB + (size_t)(t + 2) * kstep;
;             const char* a3 = a2 + kstep; const char* b3 = b2 + kstep;
;             if (last && has_next) S.a_ready(nxt);
;             PG8_LDB(B0, 0, 0); PG8_SCHED; PG8_LDA(At, 0, 0); PG8_STAGE(PG8_SA(1, 1), a1 + hstep, voffA);
;             PG8_WAIT_L(8); PG8_BAR; PG8_WAIT_L(0); PG8_MMA(0, 0, At, B0); PG8_BAR; PG8_SCHED;
.LBB0_645:
	s_ashr_i32 s75, s74, 31
	v_mov_b64_e32 v[0:1], s[0:1]
	s_lshl_b64 s[16:17], s[74:75], 19
	v_cmp_lt_i64_e32 vcc, s[66:67], v[0:1]
	s_add_u32 s66, s76, s16
	s_addc_u32 s67, s77, s17
	s_and_b64 s[16:17], vcc, exec
	s_cselect_b32 s75, s67, s79
	s_cselect_b32 s16, s66, s78
	s_ashr_i32 s73, s72, 31
	s_lshl_b64 s[18:19], s[72:73], 19
	s_add_u32 s88, s7, s18
	s_addc_u32 s89, s8, s19
	s_and_b64 s[18:19], vcc, exec
	s_cselect_b32 s17, s89, s71
	s_cselect_b32 s73, s88, s70
	s_add_u32 vcc_lo, s78, 0x40080
	s_addc_u32 vcc_hi, s79, 0
	s_add_u32 s18, s70, 0x100
	v_mov_b32_e32 v0, 0
	s_addc_u32 s19, s71, 0
	s_mov_b32 s20, -2
	v_mov_b32_e32 v1, v0
	v_mov_b32_e32 v2, v0
	v_mov_b32_e32 v3, v0
	v_mov_b32_e32 v4, v0
	v_mov_b32_e32 v5, v0
	v_mov_b32_e32 v6, v0
	v_mov_b32_e32 v7, v0
	v_mov_b32_e32 v10, v0
	v_mov_b32_e32 v11, v0
	v_mov_b32_e32 v12, v0
	v_mov_b32_e32 v13, v0
	v_mov_b32_e32 v14, v0
	v_mov_b32_e32 v15, v0
	v_mov_b32_e32 v16, v0
	v_mov_b32_e32 v17, v0
	v_mov_b32_e32 v26, v0
	v_mov_b32_e32 v27, v0
	v_mov_b32_e32 v28, v0
	v_mov_b32_e32 v29, v0
	v_mov_b32_e32 v30, v0
	v_mov_b32_e32 v31, v0
	v_mov_b32_e32 v32, v0
	v_mov_b32_e32 v33, v0
	v_mov_b32_e32 v42, v0
	v_mov_b32_e32 v43, v0
	v_mov_b32_e32 v44, v0
	v_mov_b32_e32 v45, v0
	v_mov_b32_e32 v46, v0
	v_mov_b32_e32 v47, v0
	v_mov_b32_e32 v48, v0
	v_mov_b32_e32 v49, v0
	v_mov_b32_e32 v18, v0
	v_mov_b32_e32 v19, v0
	v_mov_b32_e32 v20, v0
	v_mov_b32_e32 v21, v0
	v_mov_b32_e32 v22, v0
	v_mov_b32_e32 v23, v0
	v_mov_b32_e32 v24, v0
	v_mov_b32_e32 v25, v0
	v_mov_b32_e32 v34, v0
	v_mov_b32_e32 v35, v0
	v_mov_b32_e32 v36, v0
	v_mov_b32_e32 v37, v0
	v_mov_b32_e32 v38, v0
	v_mov_b32_e32 v39, v0
	v_mov_b32_e32 v40, v0
	v_mov_b32_e32 v41, v0
	v_mov_b32_e32 v50, v0
	v_mov_b32_e32 v51, v0
	v_mov_b32_e32 v52, v0
	v_mov_b32_e32 v53, v0
	v_mov_b32_e32 v54, v0
	v_mov_b32_e32 v55, v0
	v_mov_b32_e32 v56, v0
	v_mov_b32_e32 v57, v0
	v_mov_b32_e32 v58, v0
	v_mov_b32_e32 v59, v0
	v_mov_b32_e32 v60, v0
	v_mov_b32_e32 v61, v0
	v_mov_b32_e32 v62, v0
	v_mov_b32_e32 v63, v0
	v_mov_b32_e32 v64, v0
	v_mov_b32_e32 v65, v0
	v_mov_b32_e32 v66, v0
	v_mov_b32_e32 v67, v0
	v_mov_b32_e32 v68, v0
	v_mov_b32_e32 v69, v0
	v_mov_b32_e32 v70, v0
	v_mov_b32_e32 v71, v0
	v_mov_b32_e32 v72, v0
	v_mov_b32_e32 v73, v0
	v_mov_b32_e32 v74, v0
	v_mov_b32_e32 v75, v0
	v_mov_b32_e32 v76, v0
	v_mov_b32_e32 v77, v0
	v_mov_b32_e32 v78, v0
	v_mov_b32_e32 v79, v0
	v_mov_b32_e32 v80, v0
	v_mov_b32_e32 v81, v0
	v_mov_b32_e32 v90, v0
	v_mov_b32_e32 v91, v0
	v_mov_b32_e32 v92, v0
	v_mov_b32_e32 v93, v0
	v_mov_b32_e32 v94, v0
	v_mov_b32_e32 v95, v0
	v_mov_b32_e32 v96, v0
	v_mov_b32_e32 v97, v0
	v_mov_b32_e32 v106, v0
	v_mov_b32_e32 v107, v0
	v_mov_b32_e32 v108, v0
	v_mov_b32_e32 v109, v0
	v_mov_b32_e32 v110, v0
	v_mov_b32_e32 v111, v0
	v_mov_b32_e32 v112, v0
	v_mov_b32_e32 v113, v0
	v_mov_b32_e32 v82, v0
	v_mov_b32_e32 v83, v0
	v_mov_b32_e32 v84, v0
	v_mov_b32_e32 v85, v0
	v_mov_b32_e32 v86, v0
	v_mov_b32_e32 v87, v0
	v_mov_b32_e32 v88, v0
	v_mov_b32_e32 v89, v0
	v_mov_b32_e32 v98, v0
	v_mov_b32_e32 v99, v0
	v_mov_b32_e32 v100, v0
	v_mov_b32_e32 v101, v0
	v_mov_b32_e32 v102, v0
	v_mov_b32_e32 v103, v0
	v_mov_b32_e32 v104, v0
	v_mov_b32_e32 v105, v0
	v_mov_b32_e32 v114, v0
	v_mov_b32_e32 v115, v0
	v_mov_b32_e32 v116, v0
	v_mov_b32_e32 v117, v0
	v_mov_b32_e32 v118, v0
	v_mov_b32_e32 v119, v0
	v_mov_b32_e32 v120, v0
	v_mov_b32_e32 v121, v0
	v_mov_b32_e32 v122, v0
	v_mov_b32_e32 v123, v0
	v_mov_b32_e32 v124, v0
	v_mov_b32_e32 v125, v0
	v_mov_b32_e32 v126, v0
	v_mov_b32_e32 v127, v0
	v_mov_b32_e32 v128, v0
	v_mov_b32_e32 v129, v0
	v_add_u32_e32 v155, 0x10010, v152
	ds_read_b128 v[156:159], v155
	ds_read_b128 v[160:163], v155 offset:1024
	ds_read_b128 v[164:167], v155 offset:2048
	ds_read_b128 v[168:171], v155 offset:3072
.LBB0_646:
	s_add_u32 s21, vcc_lo, 0xfffc0080
	s_addc_u32 s22, vcc_hi, -1
	s_add_i32 s23, 16, 0x10000
	v_add_u32_e32 v155, s23, v152
	s_cmp_eq_u32 s20, 12
	s_cselect_b32 s79, s75, s22
	s_cselect_b32 s78, s16, s21
	s_cselect_b32 s71, s17, s19
	s_cselect_b32 s70, s73, s18
	v_lshl_add_u64 v[216:217], vcc, 0, v[148:149]
	s_add_i32 m0, s11, 0xc000
	ds_read_b128 v[172:175], v154
	ds_read_b128 v[188:191], v154 offset:1024
	ds_read_b128 v[192:195], v154 offset:2048
	ds_read_b128 v[196:199], v154 offset:3072
	ds_read_b128 v[200:203], v154 offset:4096
	ds_read_b128 v[204:207], v154 offset:5120
	ds_read_b128 v[208:211], v154 offset:6144
	ds_read_b128 v[212:215], v154 offset:7168
	global_load_lds_dwordx4 v[216:217], off
	v_lshl_add_u64 v[216:217], vcc, 0, v[150:151]
	s_add_i32 m0, s11, 0xe000
	s_nop 0
	global_load_lds_dwordx4 v[216:217], off
	s_waitcnt lgkmcnt(8)
	s_barrier
	s_waitcnt lgkmcnt(0)
	s_setprio 1
	s_waitcnt lgkmcnt(0)
	v_mfma_f32_16x16x32_bf16 v[126:129], v[156:159], v[172:175], v[126:129]
	v_mfma_f32_16x16x32_bf16 v[122:125], v[164:167], v[172:175], v[122:125]
	v_mfma_f32_16x16x32_bf16 v[118:121], v[156:159], v[192:195], v[118:121]
	v_mfma_f32_16x16x32_bf16 v[114:117], v[164:167], v[192:195], v[114:117]
	v_mfma_f32_16x16x32_bf16 v[102:105], v[156:159], v[200:203], v[102:105]
	v_mfma_f32_16x16x32_bf16 v[98:101], v[164:167], v[200:203], v[98:101]
	v_mfma_f32_16x16x32_bf16 v[86:89], v[156:159], v[208:211], v[86:89]
	v_mfma_f32_16x16x32_bf16 v[82:85], v[164:167], v[208:211], v[82:85]
	v_mfma_f32_16x16x32_bf16 v[126:129], v[160:163], v[188:191], v[126:129]
	v_mfma_f32_16x16x32_bf16 v[122:125], v[168:171], v[188:191], v[122:125]
	v_mfma_f32_16x16x32_bf16 v[118:121], v[160:163], v[196:199], v[118:121]
	v_mfma_f32_16x16x32_bf16 v[114:117], v[168:171], v[196:199], v[114:117]
	v_mfma_f32_16x16x32_bf16 v[102:105], v[160:163], v[204:207], v[102:105]
	v_mfma_f32_16x16x32_bf16 v[98:101], v[168:171], v[204:207], v[98:101]
	v_mfma_f32_16x16x32_bf16 v[86:89], v[160:163], v[212:215], v[86:89]
	v_mfma_f32_16x16x32_bf16 v[82:85], v[168:171], v[212:215], v[82:85]
	s_setprio 0
	s_barrier
; #define PG8_STAGE(bufoff, gbase, voff) do { _Pragma("unroll") for (int _i = 0; _i < 2; ++_i) \
;         __builtin_amdgcn_global_load_lds((const unsigned*)((const char*)(gbase) + (voff)[_i]), (LAS unsigned*)(lds + (bufoff) + ldsw + _i * 8192), 16, 0, 0); } while (0)
; #define PG8_LDA(dst, b, h) do { _Pragma("unroll") for (int m = 0; m < 4; ++m) _Pragma("unroll") for (int k = 0; k < 2; ++k) dst[m][k] = *(const LAS bf16x8*)(lds + PG8_SA(b, h) + aoff + m * 2048 + k * 1024); } while (0)
; #define PG8_LDB(dst, b, h) do { _Pragma("unroll") for (int n = 0; n < 2; ++n) _Pragma("unroll") for (int k = 0; k < 2; ++k) dst[n][k] = *(const LAS bf16x8*)(lds + PG8_SB(b, h) + boff + n * 2048 + k * 1024); } while (0)
; #define PG8_MMA(ai, bj, At, Bt) do { __builtin_amdgcn_s_setprio(1); _Pragma("unroll") for (int m = 0; m < 4; ++m) _Pragma("unroll") for (int n = 0; n < 2; ++n) _Pragma("unroll") for (int k = 0; k < 2; ++k) \
;         acc[ai][bj][m][n] = __builtin_amdgcn_mfma_f32_16x16x32_bf16(Bt[n][k], At[m][k], acc[ai][bj][m][n], 0, 0, 0); __builtin_amdgcn_s_setprio(0); } while (0)
; #define PG8_WAIT_V(n) asm volatile("s_waitcnt vmcnt(" #n ")" ::: "memory")
; #define PG8_WAIT_L(n) asm volatile("s_waitcnt lgkmcnt(" #n ")" ::: "memory")
; #define PG8_BAR __builtin_amdgcn_s_barrier()
; #define PG8_SCHED __builtin_amdgcn_sched_barrier(0)
; template <class Epi, class Sched>
; __device__ __forceinline__ void gemm_phase(LAS unsigned char* lds, const Gemm g, const Sched& S, const Epi& E) {
;     ...
;             PG8_LDB(B1, 0, 1); PG8_STAGE(PG8_SB(0, 0), b2, voffB);
;             PG8_BAR; PG8_WAIT_L(0); PG8_MMA(0, 1, At, B1); PG8_BAR;
;             PG8_LDA(At, 0, 1); PG8_STAGE(PG8_SA(0, 0), a2, voffA);
;             PG8_BAR; PG8_WAIT_L(0); PG8_MMA(1, 0, At, B0); PG8_BAR; PG8_SCHED;
;             PG8_STAGE(PG8_SB(0, 1), b2 + hstep, voffB);
;             PG8_WAIT_V(6); PG8_BAR; PG8_MMA(1, 1, At, B1); PG8_BAR;
;             PG8_LDB(B0, 1, 0); PG8_SCHED; PG8_LDA(At, 1, 0); PG8_STAGE(PG8_SA(0, 1), a2 + hstep, voffA);
;             PG8_WAIT_L(8); PG8_BAR; PG8_WAIT_L(0); PG8_MMA(0, 0, At, B0); PG8_BAR; PG8_SCHED;
	s_add_i32 s21, 16, 0x14000
	s_add_i32 s22, s23, s9
	v_add_u32_e32 v155, s21, v152
	v_lshl_add_u64 v[232:233], s[70:71], 0, v[144:145]
	s_mov_b32 m0, s22
	ds_read_b128 v[216:219], v155
	ds_read_b128 v[220:223], v155 offset:1024
	ds_read_b128 v[224:227], v155 offset:2048
	ds_read_b128 v[228:231], v155 offset:3072
	global_load_lds_dwordx4 v[232:233], off
	v_lshl_add_u64 v[234:235], s[70:71], 0, v[140:141]
	s_add_i32 m0, s22, 0x2000
	s_nop 0
	global_load_lds_dwordx4 v[234:235], off
	s_barrier
	s_waitcnt lgkmcnt(0)
	s_setprio 1
	s_waitcnt lgkmcnt(0)
	v_mfma_f32_16x16x32_bf16 v[110:113], v[216:219], v[172:175], v[110:113]
	v_mfma_f32_16x16x32_bf16 v[106:109], v[224:227], v[172:175], v[106:109]
	v_mfma_f32_16x16x32_bf16 v[94:97], v[216:219], v[192:195], v[94:97]
	v_mfma_f32_16x16x32_bf16 v[90:93], v[224:227], v[192:195], v[90:93]
	v_mfma_f32_16x16x32_bf16 v[78:81], v[216:219], v[200:203], v[78:81]
	v_mfma_f32_16x16x32_bf16 v[74:77], v[224:227], v[200:203], v[74:77]
	v_mfma_f32_16x16x32_bf16 v[70:73], v[216:219], v[208:211], v[70:73]
	v_mfma_f32_16x16x32_bf16 v[66:69], v[224:227], v[208:211], v[66:69]
	v_mfma_f32_16x16x32_bf16 v[110:113], v[220:223], v[188:191], v[110:113]
	v_mfma_f32_16x16x32_bf16 v[106:109], v[228:231], v[188:191], v[106:109]
	v_mfma_f32_16x16x32_bf16 v[94:97], v[220:223], v[196:199], v[94:97]
	v_mfma_f32_16x16x32_bf16 v[90:93], v[228:231], v[196:199], v[90:93]
	v_mfma_f32_16x16x32_bf16 v[78:81], v[220:223], v[204:207], v[78:81]
	v_mfma_f32_16x16x32_bf16 v[74:77], v[228:231], v[204:207], v[74:77]
	v_mfma_f32_16x16x32_bf16 v[70:73], v[220:223], v[212:215], v[70:73]
	v_mfma_f32_16x16x32_bf16 v[66:69], v[228:231], v[212:215], v[66:69]
	s_setprio 0
	s_mov_b32 m0, s11
	v_lshl_add_u64 v[236:237], s[78:79], 0, v[146:147]
	s_barrier
	ds_read_b128 v[172:175], v154 offset:16384
	ds_read_b128 v[188:191], v154 offset:17408
	ds_read_b128 v[192:195], v154 offset:18432
	ds_read_b128 v[196:199], v154 offset:19456
	ds_read_b128 v[200:203], v154 offset:20480
	ds_read_b128 v[204:207], v154 offset:21504
	ds_read_b128 v[208:211], v154 offset:22528
	ds_read_b128 v[212:215], v154 offset:23552
	global_load_lds_dwordx4 v[236:237], off
	v_lshl_add_u64 v[238:239], s[78:79], 0, v[142:143]
	s_mov_b32 m0, s41
	s_nop 0
	global_load_lds_dwordx4 v[238:239], off
	s_barrier
	s_waitcnt lgkmcnt(0)
	s_setprio 1
	s_waitcnt lgkmcnt(0)
	v_mfma_f32_16x16x32_bf16 v[62:65], v[156:159], v[172:175], v[62:65]
	v_mfma_f32_16x16x32_bf16 v[58:61], v[164:167], v[172:175], v[58:61]
	v_mfma_f32_16x16x32_bf16 v[54:57], v[156:159], v[192:195], v[54:57]
	v_mfma_f32_16x16x32_bf16 v[50:53], v[164:167], v[192:195], v[50:53]
	v_mfma_f32_16x16x32_bf16 v[38:41], v[156:159], v[200:203], v[38:41]
	v_mfma_f32_16x16x32_bf16 v[34:37], v[164:167], v[200:203], v[34:37]
	v_mfma_f32_16x16x32_bf16 v[22:25], v[156:159], v[208:211], v[22:25]
	v_mfma_f32_16x16x32_bf16 v[18:21], v[164:167], v[208:211], v[18:21]
	v_mfma_f32_16x16x32_bf16 v[62:65], v[160:163], v[188:191], v[62:65]
	v_mfma_f32_16x16x32_bf16 v[58:61], v[168:171], v[188:191], v[58:61]
	v_mfma_f32_16x16x32_bf16 v[54:57], v[160:163], v[196:199], v[54:57]
	v_mfma_f32_16x16x32_bf16 v[50:53], v[168:171], v[196:199], v[50:53]
	v_mfma_f32_16x16x32_bf16 v[38:41], v[160:163], v[204:207], v[38:41]
	v_mfma_f32_16x16x32_bf16 v[34:37], v[168:171], v[204:207], v[34:37]
	v_mfma_f32_16x16x32_bf16 v[22:25], v[160:163], v[212:215], v[22:25]
	v_mfma_f32_16x16x32_bf16 v[18:21], v[168:171], v[212:215], v[18:21]
	s_setprio 0
	s_barrier
	s_add_u32 s22, s70, 0x40000
	s_addc_u32 s23, s71, 0
	s_add_i32 s21, s21, s9
	v_lshl_add_u64 v[156:157], s[22:23], 0, v[144:145]
	s_mov_b32 m0, s21
	s_nop 0
	global_load_lds_dwordx4 v[156:157], off
	v_lshl_add_u64 v[156:157], s[22:23], 0, v[140:141]
	s_add_i32 m0, s21, 0x2000
	s_nop 0
	global_load_lds_dwordx4 v[156:157], off
	s_waitcnt vmcnt(6)
	s_barrier
	v_add_u32_e32 v155, 0x18010, v152
	ds_read_b128 v[156:159], v155
	ds_read_b128 v[160:163], v155 offset:1024
	ds_read_b128 v[164:167], v155 offset:2048
	ds_read_b128 v[168:171], v155 offset:3072
	s_setprio 1
	v_mfma_f32_16x16x32_bf16 v[46:49], v[216:219], v[172:175], v[46:49]
	v_mfma_f32_16x16x32_bf16 v[42:45], v[224:227], v[172:175], v[42:45]
	v_mfma_f32_16x16x32_bf16 v[30:33], v[216:219], v[192:195], v[30:33]
	v_mfma_f32_16x16x32_bf16 v[26:29], v[224:227], v[192:195], v[26:29]
	v_mfma_f32_16x16x32_bf16 v[14:17], v[216:219], v[200:203], v[14:17]
	v_mfma_f32_16x16x32_bf16 v[10:13], v[224:227], v[200:203], v[10:13]
	v_mfma_f32_16x16x32_bf16 v[4:7], v[216:219], v[208:211], v[4:7]
	v_mfma_f32_16x16x32_bf16 v[0:3], v[224:227], v[208:211], v[0:3]
	v_mfma_f32_16x16x32_bf16 v[46:49], v[220:223], v[188:191], v[46:49]
	v_mfma_f32_16x16x32_bf16 v[42:45], v[228:231], v[188:191], v[42:45]
	v_mfma_f32_16x16x32_bf16 v[30:33], v[220:223], v[196:199], v[30:33]
	v_mfma_f32_16x16x32_bf16 v[26:29], v[228:231], v[196:199], v[26:29]
	v_mfma_f32_16x16x32_bf16 v[14:17], v[220:223], v[204:207], v[14:17]
	v_mfma_f32_16x16x32_bf16 v[10:13], v[228:231], v[204:207], v[10:13]
	v_mfma_f32_16x16x32_bf16 v[4:7], v[220:223], v[212:215], v[4:7]
	v_mfma_f32_16x16x32_bf16 v[0:3], v[228:231], v[212:215], v[0:3]
	s_setprio 0
	s_add_i32 s21, 16, 0x18000
	v_add_u32_e32 v155, s21, v152
	s_barrier
	s_add_u32 s22, s78, 0x40000
	s_addc_u32 s23, s79, 0
	s_mov_b32 m0, s12
	v_lshl_add_u64 v[216:217], s[22:23], 0, v[146:147]
	ds_read_b128 v[172:175], v154 offset:32768
	ds_read_b128 v[188:191], v154 offset:33792
	ds_read_b128 v[192:195], v154 offset:34816
	ds_read_b128 v[196:199], v154 offset:35840
	ds_read_b128 v[200:203], v154 offset:36864
	ds_read_b128 v[204:207], v154 offset:37888
	ds_read_b128 v[208:211], v154 offset:38912
	ds_read_b128 v[212:215], v154 offset:39936
	global_load_lds_dwordx4 v[216:217], off
	v_lshl_add_u64 v[216:217], s[22:23], 0, v[142:143]
	s_mov_b32 m0, s13
	s_nop 0
	global_load_lds_dwordx4 v[216:217], off
	s_waitcnt lgkmcnt(8)
	s_barrier
; #define PG8_STAGE(bufoff, gbase, voff) do { _Pragma("unroll") for (int _i = 0; _i < 2; ++_i) \
;         __builtin_amdgcn_global_load_lds((const unsigned*)((const char*)(gbase) + (voff)[_i]), (LAS unsigned*)(lds + (bufoff) + ldsw + _i * 8192), 16, 0, 0); } while (0)
; #define PG8_LDA(dst, b, h) do { _Pragma("unroll") for (int m = 0; m < 4; ++m) _Pragma("unroll") for (int k = 0; k < 2; ++k) dst[m][k] = *(const LAS bf16x8*)(lds + PG8_SA(b, h) + aoff + m * 2048 + k * 1024); } while (0)
; #define PG8_LDB(dst, b, h) do { _Pragma("unroll") for (int n = 0; n < 2; ++n) _Pragma("unroll") for (int k = 0; k < 2; ++k) dst[n][k] = *(const LAS bf16x8*)(lds + PG8_SB(b, h) + boff + n * 2048 + k * 1024); } while (0)
; #define PG8_MMA(ai, bj, At, Bt) do { __builtin_amdgcn_s_setprio(1); _Pragma("unroll") for (int m = 0; m < 4; ++m) _Pragma("unroll") for (int n = 0; n < 2; ++n) _Pragma("unroll") for (int k = 0; k < 2; ++k) \
;         acc[ai][bj][m][n] = __builtin_amdgcn_mfma_f32_16x16x32_bf16(Bt[n][k], At[m][k], acc[ai][bj][m][n], 0, 0, 0); __builtin_amdgcn_s_setprio(0); } while (0)
; #define PG8_WAIT_L(n) asm volatile("s_waitcnt lgkmcnt(" #n ")" ::: "memory")
; #define PG8_BAR __builtin_amdgcn_s_barrier()
; #define PG8_SCHED __builtin_amdgcn_sched_barrier(0)
; template <class Epi, class Sched>
; __device__ __forceinline__ void gemm_phase(LAS unsigned char* lds, const Gemm g, const Sched& S, const Epi& E) {
;     ...
;             PG8_WAIT_L(8); PG8_BAR; PG8_WAIT_L(0); PG8_MMA(0, 0, At, B0); PG8_BAR; PG8_SCHED;
;             PG8_LDB(B1, 1, 1); PG8_STAGE(PG8_SB(1, 0), b3, voffB);
;             PG8_BAR; PG8_WAIT_L(0); PG8_MMA(0, 1, At, B1); PG8_BAR;
;             PG8_LDA(At, 1, 1); PG8_STAGE(PG8_SA(1, 0), a3, voffA);
;             PG8_BAR; PG8_WAIT_L(0); PG8_MMA(1, 0, At, B0); PG8_BAR; PG8_SCHED;
;             PG8_STAGE(PG8_SB(1, 1), b3 + hstep, voffB);
	s_waitcnt lgkmcnt(0)
	s_setprio 1
	s_waitcnt lgkmcnt(0)
	v_mfma_f32_16x16x32_bf16 v[126:129], v[156:159], v[172:175], v[126:129]
	v_mfma_f32_16x16x32_bf16 v[122:125], v[164:167], v[172:175], v[122:125]
	v_mfma_f32_16x16x32_bf16 v[118:121], v[156:159], v[192:195], v[118:121]
	v_mfma_f32_16x16x32_bf16 v[114:117], v[164:167], v[192:195], v[114:117]
	v_mfma_f32_16x16x32_bf16 v[102:105], v[156:159], v[200:203], v[102:105]
	v_mfma_f32_16x16x32_bf16 v[98:101], v[164:167], v[200:203], v[98:101]
	v_mfma_f32_16x16x32_bf16 v[86:89], v[156:159], v[208:211], v[86:89]
	v_mfma_f32_16x16x32_bf16 v[82:85], v[164:167], v[208:211], v[82:85]
	v_mfma_f32_16x16x32_bf16 v[126:129], v[160:163], v[188:191], v[126:129]
	v_mfma_f32_16x16x32_bf16 v[122:125], v[168:171], v[188:191], v[122:125]
	v_mfma_f32_16x16x32_bf16 v[118:121], v[160:163], v[196:199], v[118:121]
	v_mfma_f32_16x16x32_bf16 v[114:117], v[168:171], v[196:199], v[114:117]
	v_mfma_f32_16x16x32_bf16 v[102:105], v[160:163], v[204:207], v[102:105]
	v_mfma_f32_16x16x32_bf16 v[98:101], v[168:171], v[204:207], v[98:101]
	v_mfma_f32_16x16x32_bf16 v[86:89], v[160:163], v[212:215], v[86:89]
	v_mfma_f32_16x16x32_bf16 v[82:85], v[168:171], v[212:215], v[82:85]
	s_setprio 0
	s_barrier
	s_add_i32 s78, 16, 0x1c000
	s_add_i32 s21, s21, s9
	v_add_u32_e32 v155, s78, v152
	v_lshl_add_u64 v[232:233], v[232:233], 0, s[94:95]
	s_mov_b32 m0, s21
	ds_read_b128 v[216:219], v155
	ds_read_b128 v[220:223], v155 offset:1024
	ds_read_b128 v[224:227], v155 offset:2048
	ds_read_b128 v[228:231], v155 offset:3072
	global_load_lds_dwordx4 v[232:233], off
	v_lshl_add_u64 v[232:233], v[234:235], 0, s[94:95]
	s_add_i32 m0, s21, 0x2000
	s_nop 0
	global_load_lds_dwordx4 v[232:233], off
	s_barrier
	s_waitcnt lgkmcnt(0)
	s_setprio 1
	s_waitcnt lgkmcnt(0)
	v_mfma_f32_16x16x32_bf16 v[110:113], v[216:219], v[172:175], v[110:113]
	v_mfma_f32_16x16x32_bf16 v[106:109], v[224:227], v[172:175], v[106:109]
	v_mfma_f32_16x16x32_bf16 v[94:97], v[216:219], v[192:195], v[94:97]
	v_mfma_f32_16x16x32_bf16 v[90:93], v[224:227], v[192:195], v[90:93]
	v_mfma_f32_16x16x32_bf16 v[78:81], v[216:219], v[200:203], v[78:81]
	v_mfma_f32_16x16x32_bf16 v[74:77], v[224:227], v[200:203], v[74:77]
	v_mfma_f32_16x16x32_bf16 v[70:73], v[216:219], v[208:211], v[70:73]
	v_mfma_f32_16x16x32_bf16 v[66:69], v[224:227], v[208:211], v[66:69]
	v_mfma_f32_16x16x32_bf16 v[110:113], v[220:223], v[188:191], v[110:113]
	v_mfma_f32_16x16x32_bf16 v[106:109], v[228:231], v[188:191], v[106:109]
	v_mfma_f32_16x16x32_bf16 v[94:97], v[220:223], v[196:199], v[94:97]
	v_mfma_f32_16x16x32_bf16 v[90:93], v[228:231], v[196:199], v[90:93]
	v_mfma_f32_16x16x32_bf16 v[78:81], v[220:223], v[204:207], v[78:81]
	v_mfma_f32_16x16x32_bf16 v[74:77], v[228:231], v[204:207], v[74:77]
	v_mfma_f32_16x16x32_bf16 v[70:73], v[220:223], v[212:215], v[70:73]
	v_mfma_f32_16x16x32_bf16 v[66:69], v[228:231], v[212:215], v[66:69]
	s_setprio 0
	s_mov_b32 m0, s14
	v_lshl_add_u64 v[232:233], v[236:237], 0, s[94:95]
	s_barrier
	ds_read_b128 v[172:175], v154 offset:49152
	ds_read_b128 v[188:191], v154 offset:50176
	ds_read_b128 v[192:195], v154 offset:51200
	ds_read_b128 v[196:199], v154 offset:52224
	ds_read_b128 v[200:203], v154 offset:53248
	ds_read_b128 v[204:207], v154 offset:54272
	ds_read_b128 v[208:211], v154 offset:55296
	ds_read_b128 v[212:215], v154 offset:56320
	global_load_lds_dwordx4 v[232:233], off
	v_lshl_add_u64 v[232:233], v[238:239], 0, s[94:95]
	s_mov_b32 m0, s15
	s_nop 0
	global_load_lds_dwordx4 v[232:233], off
	s_barrier
	s_waitcnt lgkmcnt(0)
	s_setprio 1
	s_waitcnt lgkmcnt(0)
	v_mfma_f32_16x16x32_bf16 v[62:65], v[156:159], v[172:175], v[62:65]
	v_mfma_f32_16x16x32_bf16 v[58:61], v[164:167], v[172:175], v[58:61]
	v_mfma_f32_16x16x32_bf16 v[54:57], v[156:159], v[192:195], v[54:57]
	v_mfma_f32_16x16x32_bf16 v[50:53], v[164:167], v[192:195], v[50:53]
	v_mfma_f32_16x16x32_bf16 v[38:41], v[156:159], v[200:203], v[38:41]
	v_mfma_f32_16x16x32_bf16 v[34:37], v[164:167], v[200:203], v[34:37]
	v_mfma_f32_16x16x32_bf16 v[22:25], v[156:159], v[208:211], v[22:25]
	v_mfma_f32_16x16x32_bf16 v[18:21], v[164:167], v[208:211], v[18:21]
	v_mfma_f32_16x16x32_bf16 v[62:65], v[160:163], v[188:191], v[62:65]
	v_mfma_f32_16x16x32_bf16 v[58:61], v[168:171], v[188:191], v[58:61]
	v_mfma_f32_16x16x32_bf16 v[54:57], v[160:163], v[196:199], v[54:57]
	v_mfma_f32_16x16x32_bf16 v[50:53], v[168:171], v[196:199], v[50:53]
	v_mfma_f32_16x16x32_bf16 v[38:41], v[160:163], v[204:207], v[38:41]
	v_mfma_f32_16x16x32_bf16 v[34:37], v[168:171], v[204:207], v[34:37]
	v_mfma_f32_16x16x32_bf16 v[22:25], v[160:163], v[212:215], v[22:25]
	v_mfma_f32_16x16x32_bf16 v[18:21], v[168:171], v[212:215], v[18:21]
	s_setprio 0
	s_barrier
	s_add_u32 s22, s70, 0x40080
	s_addc_u32 s23, s71, 0
	s_add_i32 s21, s78, s9
	v_lshl_add_u64 v[156:157], s[22:23], 0, v[144:145]
	s_mov_b32 m0, s21
	s_nop 0
	global_load_lds_dwordx4 v[156:157], off
	v_lshl_add_u64 v[156:157], s[22:23], 0, v[140:141]
	s_add_i32 m0, s21, 0x2000
	s_nop 0
	global_load_lds_dwordx4 v[156:157], off
	s_waitcnt vmcnt(6)
	s_barrier
; __device__ __forceinline__ unsigned pk_bf16(float a, float b) { f32x2 v = {a, b}; bf2_t r = __builtin_convertvector(v, bf2_t); return __builtin_bit_cast(unsigned, r); }
; #define PG8_MMA(ai, bj, At, Bt) do { __builtin_amdgcn_s_setprio(1); _Pragma("unroll") for (int m = 0; m < 4; ++m) _Pragma("unroll") for (int n = 0; n < 2; ++n) _Pragma("unroll") for (int k = 0; k < 2; ++k) \
;         acc[ai][bj][m][n] = __builtin_amdgcn_mfma_f32_16x16x32_bf16(Bt[n][k], At[m][k], acc[ai][bj][m][n], 0, 0, 0); __builtin_amdgcn_s_setprio(0); } while (0)
; #define PG8_WAIT_V(n) asm volatile("s_waitcnt vmcnt(" #n ")" ::: "memory")
; #define PG8_BAR __builtin_amdgcn_s_barrier()
;     __device__ __forceinline__ void operator()(const f32x4 (&acc)[2][2][4][2], const Unit& u, int wr, int wc, int fr, int fq) const {
;         const int row0 = u.pm * BM + wr * 64 + fr; int colt = u.pn * BM; bf16_t* base = O;
;         if (split_cols) { const int t = colt / split_cols; base += (size_t)t * split_stride; colt -= t * split_cols; }
;         const int col0 = colt + wc * 32 + 8 * fq;
; #pragma unroll
;         for (int ai = 0; ai < 2; ++ai)
; #pragma unroll
;             for (int m = 0; m < 4; ++m) { const int row = row0 + ai * HALF + m * 16;
;                 bf16_t* rowp = slot_stride ? base + (size_t)(colt >> 7) * slot_stride + (size_t)row * 128 + wc * 32 + 8 * fq : base + (size_t)row * ldc + col0;
; #pragma unroll
;                 for (int bj = 0; bj < 2; ++bj) { const f32x4 v0 = acc[ai][bj][m][0], v1 = acc[ai][bj][m][1];
;                     u32x4 w; w.x = pk_bf16(v0[0], v0[1]); w.y = pk_bf16(v0[2], v0[3]); w.z = pk_bf16(v1[0], v1[1]); w.w = pk_bf16(v1[2], v1[3]);
;                     *(u32x4*)(rowp + (slot_stride ? (size_t)bj * slot_stride : (size_t)bj * HALF)) = w; } }
; template <class Epi, class Sched>
; __device__ __forceinline__ void gemm_phase(LAS unsigned char* lds, const Gemm g, const Sched& S, const Epi& E) {
;     ...
;             PG8_WAIT_V(6); PG8_BAR; PG8_MMA(1, 1, At, B1); PG8_BAR;
;         }
;         E(acc, cur, wr, wc, fr, fq); S.done(cur);
;         if (!has_next) break;
	v_add_u32_e32 v155, 0x10010, v152
	ds_read_b128 v[156:159], v155
	ds_read_b128 v[160:163], v155 offset:1024
	ds_read_b128 v[164:167], v155 offset:2048
	ds_read_b128 v[168:171], v155 offset:3072
	s_setprio 1
	v_mfma_f32_16x16x32_bf16 v[46:49], v[216:219], v[172:175], v[46:49]
	v_mfma_f32_16x16x32_bf16 v[42:45], v[224:227], v[172:175], v[42:45]
	v_mfma_f32_16x16x32_bf16 v[30:33], v[216:219], v[192:195], v[30:33]
	v_mfma_f32_16x16x32_bf16 v[26:29], v[224:227], v[192:195], v[26:29]
	v_mfma_f32_16x16x32_bf16 v[14:17], v[216:219], v[200:203], v[14:17]
	v_mfma_f32_16x16x32_bf16 v[10:13], v[224:227], v[200:203], v[10:13]
	v_mfma_f32_16x16x32_bf16 v[4:7], v[216:219], v[208:211], v[4:7]
	v_mfma_f32_16x16x32_bf16 v[0:3], v[224:227], v[208:211], v[0:3]
	v_mfma_f32_16x16x32_bf16 v[46:49], v[220:223], v[188:191], v[46:49]
	v_mfma_f32_16x16x32_bf16 v[42:45], v[228:231], v[188:191], v[42:45]
	v_mfma_f32_16x16x32_bf16 v[30:33], v[220:223], v[196:199], v[30:33]
	v_mfma_f32_16x16x32_bf16 v[26:29], v[228:231], v[196:199], v[26:29]
	v_mfma_f32_16x16x32_bf16 v[14:17], v[220:223], v[204:207], v[14:17]
	v_mfma_f32_16x16x32_bf16 v[10:13], v[228:231], v[204:207], v[10:13]
	v_mfma_f32_16x16x32_bf16 v[4:7], v[220:223], v[212:215], v[4:7]
	v_mfma_f32_16x16x32_bf16 v[0:3], v[228:231], v[212:215], v[0:3]
	s_setprio 0
	s_add_i32 s20, s20, 2
	s_add_u32 vcc_lo, vcc_lo, 0x100
	s_addc_u32 vcc_hi, vcc_hi, 0
	s_add_u32 s18, s18, 0x100
	s_addc_u32 s19, s19, 0
	s_cmp_gt_u32 s20, 13
	s_barrier
	s_cbranch_scc0 .LBB0_646
	s_waitcnt lgkmcnt(0)
	s_mul_hi_i32 s16, s40, 0x2e8ba2e9
	s_lshr_b32 s17, s16, 31
	s_ashr_i32 s16, s16, 1
	s_add_i32 s19, s16, s17
	s_lshl_b32 s18, s40, 8
	s_mul_i32 s16, s19, 0xbb00000
	s_mul_hi_i32 s17, s19, 0xbb00000
	s_add_u32 s16, s82, s16
	s_mulk_i32 s19, 0xf500
	s_addc_u32 s17, s83, s17
	s_add_i32 s19, s19, s18
	v_or_b32_e32 v156, s19, v153
	v_lshl_add_u32 v155, s42, 8, v9
	v_ashrrev_i32_e32 v157, 31, v156
	v_lshl_add_u64 v[156:157], v[156:157], 1, s[16:17]
	v_cvt_pk_bf16_f32 v70, v70, v71
	v_cvt_pk_bf16_f32 v71, v72, v73
	v_cvt_pk_bf16_f32 v72, v66, v67
	v_add_u32_e32 v66, 0x80, v155
	v_mad_i64_i32 v[158:159], s[16:17], v155, s81, v[156:157]
	v_cvt_pk_bf16_f32 v110, v110, v111
	v_cvt_pk_bf16_f32 v111, v112, v113
	v_cvt_pk_bf16_f32 v112, v106, v107
	v_cvt_pk_bf16_f32 v113, v108, v109
	v_or_b32_e32 v106, 16, v155
	v_mad_i64_i32 v[66:67], s[16:17], v66, s81, v[156:157]
	v_cvt_pk_bf16_f32 v46, v46, v47
	v_cvt_pk_bf16_f32 v47, v48, v49
	v_cvt_pk_bf16_f32 v48, v42, v43
	v_cvt_pk_bf16_f32 v49, v44, v45
	v_add_u32_e32 v42, 0x90, v155
	global_store_dwordx4 v[158:159], v[110:113], off offset:256
	v_cvt_pk_bf16_f32 v94, v94, v95
	v_cvt_pk_bf16_f32 v95, v96, v97
	v_mad_i64_i32 v[110:111], s[16:17], v106, s81, v[156:157]
	v_cvt_pk_bf16_f32 v96, v90, v91
	v_cvt_pk_bf16_f32 v97, v92, v93
	v_or_b32_e32 v90, 32, v155
	global_store_dwordx4 v[66:67], v[46:49], off offset:256
	v_cvt_pk_bf16_f32 v30, v30, v31
	v_cvt_pk_bf16_f32 v31, v32, v33
	v_mad_i64_i32 v[46:47], s[16:17], v42, s81, v[156:157]
	v_cvt_pk_bf16_f32 v32, v26, v27
	v_cvt_pk_bf16_f32 v33, v28, v29
	v_add_u32_e32 v26, 0xa0, v155
	global_store_dwordx4 v[110:111], v[94:97], off offset:256
	v_cvt_pk_bf16_f32 v78, v78, v79
	v_cvt_pk_bf16_f32 v79, v80, v81
	v_mad_i64_i32 v[94:95], s[16:17], v90, s81, v[156:157]
	v_cvt_pk_bf16_f32 v80, v74, v75
	v_cvt_pk_bf16_f32 v81, v76, v77
	v_or_b32_e32 v74, 48, v155
	global_store_dwordx4 v[46:47], v[30:33], off offset:256
	v_cvt_pk_bf16_f32 v14, v14, v15
	v_cvt_pk_bf16_f32 v15, v16, v17
	v_mad_i64_i32 v[30:31], s[16:17], v26, s81, v[156:157]
	v_cvt_pk_bf16_f32 v16, v10, v11
	v_cvt_pk_bf16_f32 v17, v12, v13
	v_add_u32_e32 v10, 0xb0, v155
	v_cvt_pk_bf16_f32 v126, v126, v127
	v_cvt_pk_bf16_f32 v127, v128, v129
	v_cvt_pk_bf16_f32 v128, v122, v123
	v_cvt_pk_bf16_f32 v129, v124, v125
	v_cvt_pk_bf16_f32 v106, v118, v119
	v_cvt_pk_bf16_f32 v107, v120, v121
	v_cvt_pk_bf16_f32 v108, v114, v115
	v_cvt_pk_bf16_f32 v109, v116, v117
	v_cvt_pk_bf16_f32 v90, v102, v103
	v_cvt_pk_bf16_f32 v91, v104, v105
	v_cvt_pk_bf16_f32 v92, v98, v99
	v_cvt_pk_bf16_f32 v93, v100, v101
	global_store_dwordx4 v[94:95], v[78:81], off offset:256
	v_cvt_pk_bf16_f32 v75, v88, v89
	v_cvt_pk_bf16_f32 v76, v82, v83
	v_mad_i64_i32 v[78:79], s[16:17], v74, s81, v[156:157]
	v_cvt_pk_bf16_f32 v74, v86, v87
	v_cvt_pk_bf16_f32 v77, v84, v85
	v_cvt_pk_bf16_f32 v73, v68, v69
	v_cvt_pk_bf16_f32 v62, v62, v63
	v_cvt_pk_bf16_f32 v63, v64, v65
	v_cvt_pk_bf16_f32 v64, v58, v59
	v_cvt_pk_bf16_f32 v65, v60, v61
	v_cvt_pk_bf16_f32 v42, v54, v55
	v_cvt_pk_bf16_f32 v43, v56, v57
	v_cvt_pk_bf16_f32 v44, v50, v51
	v_cvt_pk_bf16_f32 v45, v52, v53
	v_cvt_pk_bf16_f32 v26, v38, v39
	v_cvt_pk_bf16_f32 v27, v40, v41
	v_cvt_pk_bf16_f32 v28, v34, v35
	v_cvt_pk_bf16_f32 v29, v36, v37
	global_store_dwordx4 v[30:31], v[14:17], off offset:256
	v_cvt_pk_bf16_f32 v11, v24, v25
	v_cvt_pk_bf16_f32 v12, v18, v19
	v_mad_i64_i32 v[14:15], s[16:17], v10, s81, v[156:157]
	v_cvt_pk_bf16_f32 v10, v22, v23
	v_cvt_pk_bf16_f32 v13, v20, v21
	v_cvt_pk_bf16_f32 v4, v4, v5
	v_cvt_pk_bf16_f32 v5, v6, v7
	v_cvt_pk_bf16_f32 v6, v0, v1
	v_cvt_pk_bf16_f32 v7, v2, v3
	s_and_b64 vcc, exec, s[38:39]
	s_mov_b32 s40, s72
	s_mov_b32 s42, s74
	s_mov_b64 s[70:71], s[88:89]
	s_mov_b64 s[78:79], s[66:67]
	global_store_dwordx4 v[158:159], v[126:129], off
	global_store_dwordx4 v[110:111], v[106:109], off
	global_store_dwordx4 v[94:95], v[90:93], off
	global_store_dwordx4 v[78:79], v[74:77], off
	global_store_dwordx4 v[78:79], v[70:73], off offset:256
	global_store_dwordx4 v[66:67], v[62:65], off
	global_store_dwordx4 v[46:47], v[42:45], off
	global_store_dwordx4 v[30:31], v[26:29], off
	global_store_dwordx4 v[14:15], v[10:13], off
	global_store_dwordx4 v[14:15], v[4:7], off offset:256
	s_cbranch_vccz .LBB0_643
	s_waitcnt vmcnt(0)
	s_cmpk_gt_u32 s6, 0xff
	s_cbranch_scc1 .LBB0_650
	s_barrier

; #define PG8_STAGE(bufoff, gbase, voff) do { _Pragma("unroll") for (int _i = 0; _i < 2; ++_i) \
;         __builtin_amdgcn_global_load_lds((const unsigned*)((const char*)(gbase) + (voff)[_i]), (LAS unsigned*)(lds + (bufoff) + ldsw + _i * 8192), 16, 0, 0); } while (0)
; #define PG8_LDA(dst, b, h) do { _Pragma("unroll") for (int m = 0; m < 4; ++m) _Pragma("unroll") for (int k = 0; k < 2; ++k) dst[m][k] = *(const LAS bf16x8*)(lds + PG8_SA(b, h) + aoff + m * 2048 + k * 1024); } while (0)
; #define PG8_LDB(dst, b, h) do { _Pragma("unroll") for (int n = 0; n < 2; ++n) _Pragma("unroll") for (int k = 0; k < 2; ++k) dst[n][k] = *(const LAS bf16x8*)(lds + PG8_SB(b, h) + boff + n * 2048 + k * 1024); } while (0)
; template <class Epi, class Sched>
; __device__ __forceinline__ void gemm_phase(LAS unsigned char* lds, const Gemm g, const Sched& S, const Epi& E) {
;     ...
;                 for (int n = 0; n < 2; ++n) acc[a][b][m][n] = (f32x4){0.f, 0.f, 0.f, 0.f};
;     bf16x8 At[4][2], B0[2][2], B1[2][2];
;     const char* cA = (const char*)g.A + (size_t)cur.pm * tstep; const char* cB = (const char*)g.Bt + (size_t)cur.pn * tstep;
;     S.a_ready(cur);
;     PG8_STAGE(PG8_SB(0, 0), cB, voffB); PG8_STAGE(PG8_SA(0, 0), cA, voffA); PG8_STAGE(PG8_SB(0, 1), cB + hstep, voffB); PG8_STAGE(PG8_SA(0, 1), cA + hstep, voffA);
;     if (wr == 1) PG8_BAR;
;     PG8_WAIT_V(4); PG8_BAR;
;     PG8_STAGE(PG8_SB(1, 0), cB + kstep, voffB); PG8_STAGE(PG8_SA(1, 0), cA + kstep, voffA); PG8_STAGE(PG8_SB(1, 1), cB + hstep + kstep, voffB);
;     PG8_WAIT_V(6); PG8_BAR;
;     for (;;) {
;         const bool has_next = S.next(ui + 1, nxt);
;         const char* nA = has_next ? (const char*)g.A + (size_t)nxt.pm * tstep : cA; const char* nB = has_next ? (const char*)g.Bt + (size_t)nxt.pn * tstep : cB;
;         for (int t = 0; t < nt; t += 2) {
;             const bool last = (t == nt - 2);
;             const char* a1 = cA + (size_t)(t + 1) * kstep;
;             const char* a2 = last ? nA : cA + (size_t)(t + 2) * kstep; const char* b2 = last ? nB : cB + (size_t)(t + 2) * kstep;
;             const char* a3 = a2 + kstep; const char* b3 = b2 + kstep;
;             if (last && has_next) S.a_ready(nxt);
;             PG8_LDB(B0, 0, 0); PG8_SCHED; PG8_LDA(At, 0, 0); PG8_STAGE(PG8_SA(1, 1), a1 + hstep, voffA);
;             PG8_WAIT_L(8); PG8_BAR; PG8_WAIT_L(0); PG8_MMA(0, 0, At, B0); PG8_BAR; PG8_SCHED;
.LBB0_824:
	s_add_u32 s16, s72, 0x100
	v_mov_b32_e32 v0, 0
	s_addc_u32 s17, s73, 0
	s_mov_b32 s18, -2
	v_mov_b32_e32 v1, v0
	v_mov_b32_e32 v2, v0
	v_mov_b32_e32 v3, v0
	v_mov_b32_e32 v4, v0
	v_mov_b32_e32 v5, v0
	v_mov_b32_e32 v6, v0
	v_mov_b32_e32 v7, v0
	v_mov_b32_e32 v10, v0
	v_mov_b32_e32 v11, v0
	v_mov_b32_e32 v12, v0
	v_mov_b32_e32 v13, v0
	v_mov_b32_e32 v14, v0
	v_mov_b32_e32 v15, v0
	v_mov_b32_e32 v16, v0
	v_mov_b32_e32 v17, v0
	v_mov_b32_e32 v26, v0
	v_mov_b32_e32 v27, v0
	v_mov_b32_e32 v28, v0
	v_mov_b32_e32 v29, v0
	v_mov_b32_e32 v30, v0
	v_mov_b32_e32 v31, v0
	v_mov_b32_e32 v32, v0
	v_mov_b32_e32 v33, v0
	v_mov_b32_e32 v42, v0
	v_mov_b32_e32 v43, v0
	v_mov_b32_e32 v44, v0
	v_mov_b32_e32 v45, v0
	v_mov_b32_e32 v46, v0
	v_mov_b32_e32 v47, v0
	v_mov_b32_e32 v48, v0
	v_mov_b32_e32 v49, v0
	v_mov_b32_e32 v18, v0
	v_mov_b32_e32 v19, v0
	v_mov_b32_e32 v20, v0
	v_mov_b32_e32 v21, v0
	v_mov_b32_e32 v22, v0
	v_mov_b32_e32 v23, v0
	v_mov_b32_e32 v24, v0
	v_mov_b32_e32 v25, v0
	v_mov_b32_e32 v34, v0
	v_mov_b32_e32 v35, v0
	v_mov_b32_e32 v36, v0
	v_mov_b32_e32 v37, v0
	v_mov_b32_e32 v38, v0
	v_mov_b32_e32 v39, v0
	v_mov_b32_e32 v40, v0
	v_mov_b32_e32 v41, v0
	v_mov_b32_e32 v50, v0
	v_mov_b32_e32 v51, v0
	v_mov_b32_e32 v52, v0
	v_mov_b32_e32 v53, v0
	v_mov_b32_e32 v54, v0
	v_mov_b32_e32 v55, v0
	v_mov_b32_e32 v56, v0
	v_mov_b32_e32 v57, v0
	v_mov_b32_e32 v58, v0
	v_mov_b32_e32 v59, v0
	v_mov_b32_e32 v60, v0
	v_mov_b32_e32 v61, v0
	v_mov_b32_e32 v62, v0
	v_mov_b32_e32 v63, v0
	v_mov_b32_e32 v64, v0
	v_mov_b32_e32 v65, v0
	v_mov_b32_e32 v66, v0
	v_mov_b32_e32 v67, v0
	v_mov_b32_e32 v68, v0
	v_mov_b32_e32 v69, v0
	v_mov_b32_e32 v70, v0
	v_mov_b32_e32 v71, v0
	v_mov_b32_e32 v72, v0
	v_mov_b32_e32 v73, v0
	v_mov_b32_e32 v74, v0
	v_mov_b32_e32 v75, v0
	v_mov_b32_e32 v76, v0
	v_mov_b32_e32 v77, v0
	v_mov_b32_e32 v78, v0
	v_mov_b32_e32 v79, v0
	v_mov_b32_e32 v80, v0
	v_mov_b32_e32 v81, v0
	v_mov_b32_e32 v90, v0
	v_mov_b32_e32 v91, v0
	v_mov_b32_e32 v92, v0
	v_mov_b32_e32 v93, v0
	v_mov_b32_e32 v94, v0
	v_mov_b32_e32 v95, v0
	v_mov_b32_e32 v96, v0
	v_mov_b32_e32 v97, v0
	v_mov_b32_e32 v106, v0
	v_mov_b32_e32 v107, v0
	v_mov_b32_e32 v108, v0
	v_mov_b32_e32 v109, v0
	v_mov_b32_e32 v110, v0
	v_mov_b32_e32 v111, v0
	v_mov_b32_e32 v112, v0
	v_mov_b32_e32 v113, v0
	v_mov_b32_e32 v82, v0
	v_mov_b32_e32 v83, v0
	v_mov_b32_e32 v84, v0
	v_mov_b32_e32 v85, v0
	v_mov_b32_e32 v86, v0
	v_mov_b32_e32 v87, v0
	v_mov_b32_e32 v88, v0
	v_mov_b32_e32 v89, v0
	v_mov_b32_e32 v98, v0
	v_mov_b32_e32 v99, v0
	v_mov_b32_e32 v100, v0
	v_mov_b32_e32 v101, v0
	v_mov_b32_e32 v102, v0
	v_mov_b32_e32 v103, v0
	v_mov_b32_e32 v104, v0
	v_mov_b32_e32 v105, v0
	v_mov_b32_e32 v114, v0
	v_mov_b32_e32 v115, v0
	v_mov_b32_e32 v116, v0
	v_mov_b32_e32 v117, v0
	v_mov_b32_e32 v118, v0
	v_mov_b32_e32 v119, v0
	v_mov_b32_e32 v120, v0
	v_mov_b32_e32 v121, v0
	v_mov_b32_e32 v122, v0
	v_mov_b32_e32 v123, v0
	v_mov_b32_e32 v124, v0
	v_mov_b32_e32 v125, v0
	v_mov_b32_e32 v126, v0
	v_mov_b32_e32 v127, v0
	v_mov_b32_e32 v128, v0
	v_mov_b32_e32 v129, v0
	v_add_u32_e32 v155, 0x10010, v152
	ds_read_b128 v[156:159], v155
	ds_read_b128 v[160:163], v155 offset:1024
	ds_read_b128 v[164:167], v155 offset:2048
	ds_read_b128 v[168:171], v155 offset:3072
.LBB0_825:
	s_add_u32 s72, s42, 0x100
	s_addc_u32 s73, s43, 0
	s_add_i32 s19, 16, 0x10000
	v_add_u32_e32 v155, s19, v152
	s_cmp_eq_u32 s18, 40
	s_cselect_b32 s71, s41, s73
	s_cselect_b32 s70, s40, s72
	s_cselect_b32 s67, s1, s17
	s_cselect_b32 s66, s0, s16
	v_lshl_add_u64 v[216:217], s[42:43], 0, v[148:149]
	s_add_i32 m0, s11, 0xc000
	ds_read_b128 v[172:175], v154
	ds_read_b128 v[188:191], v154 offset:1024
	ds_read_b128 v[192:195], v154 offset:2048
	ds_read_b128 v[196:199], v154 offset:3072
	ds_read_b128 v[200:203], v154 offset:4096
	ds_read_b128 v[204:207], v154 offset:5120
	ds_read_b128 v[208:211], v154 offset:6144
	ds_read_b128 v[212:215], v154 offset:7168
	global_load_lds_dwordx4 v[216:217], off
	v_lshl_add_u64 v[216:217], s[42:43], 0, v[150:151]
	s_add_i32 m0, s11, 0xe000
	s_nop 0
	global_load_lds_dwordx4 v[216:217], off
	s_waitcnt lgkmcnt(8)
	s_barrier
	s_waitcnt lgkmcnt(0)
	s_setprio 1
	s_waitcnt lgkmcnt(0)
	v_mfma_f32_16x16x32_bf16 v[126:129], v[156:159], v[172:175], v[126:129]
	v_mfma_f32_16x16x32_bf16 v[122:125], v[164:167], v[172:175], v[122:125]
	v_mfma_f32_16x16x32_bf16 v[118:121], v[156:159], v[192:195], v[118:121]
	v_mfma_f32_16x16x32_bf16 v[114:117], v[164:167], v[192:195], v[114:117]
	v_mfma_f32_16x16x32_bf16 v[102:105], v[156:159], v[200:203], v[102:105]
	v_mfma_f32_16x16x32_bf16 v[98:101], v[164:167], v[200:203], v[98:101]
	v_mfma_f32_16x16x32_bf16 v[86:89], v[156:159], v[208:211], v[86:89]
	v_mfma_f32_16x16x32_bf16 v[82:85], v[164:167], v[208:211], v[82:85]
	v_mfma_f32_16x16x32_bf16 v[126:129], v[160:163], v[188:191], v[126:129]
	v_mfma_f32_16x16x32_bf16 v[122:125], v[168:171], v[188:191], v[122:125]
	v_mfma_f32_16x16x32_bf16 v[118:121], v[160:163], v[196:199], v[118:121]
	v_mfma_f32_16x16x32_bf16 v[114:117], v[168:171], v[196:199], v[114:117]
	v_mfma_f32_16x16x32_bf16 v[102:105], v[160:163], v[204:207], v[102:105]
	v_mfma_f32_16x16x32_bf16 v[98:101], v[168:171], v[204:207], v[98:101]
	v_mfma_f32_16x16x32_bf16 v[86:89], v[160:163], v[212:215], v[86:89]
	v_mfma_f32_16x16x32_bf16 v[82:85], v[168:171], v[212:215], v[82:85]
	s_setprio 0
	s_barrier
	s_add_i32 s22, 16, 0x14000
	s_add_i32 s19, s19, s9
	v_add_u32_e32 v155, s22, v152
	v_lshl_add_u64 v[232:233], s[66:67], 0, v[144:145]
	s_mov_b32 m0, s19
	ds_read_b128 v[216:219], v155
	ds_read_b128 v[220:223], v155 offset:1024
	ds_read_b128 v[224:227], v155 offset:2048
	ds_read_b128 v[228:231], v155 offset:3072
	global_load_lds_dwordx4 v[232:233], off
	v_lshl_add_u64 v[234:235], s[66:67], 0, v[140:141]
	s_add_i32 m0, s19, 0x2000
	s_nop 0
	global_load_lds_dwordx4 v[234:235], off
	s_barrier
; #define PG8_STAGE(bufoff, gbase, voff) do { _Pragma("unroll") for (int _i = 0; _i < 2; ++_i) \
;         __builtin_amdgcn_global_load_lds((const unsigned*)((const char*)(gbase) + (voff)[_i]), (LAS unsigned*)(lds + (bufoff) + ldsw + _i * 8192), 16, 0, 0); } while (0)
; #define PG8_LDA(dst, b, h) do { _Pragma("unroll") for (int m = 0; m < 4; ++m) _Pragma("unroll") for (int k = 0; k < 2; ++k) dst[m][k] = *(const LAS bf16x8*)(lds + PG8_SA(b, h) + aoff + m * 2048 + k * 1024); } while (0)
; #define PG8_LDB(dst, b, h) do { _Pragma("unroll") for (int n = 0; n < 2; ++n) _Pragma("unroll") for (int k = 0; k < 2; ++k) dst[n][k] = *(const LAS bf16x8*)(lds + PG8_SB(b, h) + boff + n * 2048 + k * 1024); } while (0)
; #define PG8_MMA(ai, bj, At, Bt) do { __builtin_amdgcn_s_setprio(1); _Pragma("unroll") for (int m = 0; m < 4; ++m) _Pragma("unroll") for (int n = 0; n < 2; ++n) _Pragma("unroll") for (int k = 0; k < 2; ++k) \
;         acc[ai][bj][m][n] = __builtin_amdgcn_mfma_f32_16x16x32_bf16(Bt[n][k], At[m][k], acc[ai][bj][m][n], 0, 0, 0); __builtin_amdgcn_s_setprio(0); } while (0)
; #define PG8_WAIT_V(n) asm volatile("s_waitcnt vmcnt(" #n ")" ::: "memory")
; #define PG8_WAIT_L(n) asm volatile("s_waitcnt lgkmcnt(" #n ")" ::: "memory")
; #define PG8_BAR __builtin_amdgcn_s_barrier()
; #define PG8_SCHED __builtin_amdgcn_sched_barrier(0)
; template <class Epi, class Sched>
; __device__ __forceinline__ void gemm_phase(LAS unsigned char* lds, const Gemm g, const Sched& S, const Epi& E) {
;     ...
;             PG8_BAR; PG8_WAIT_L(0); PG8_MMA(1, 0, At, B0); PG8_BAR; PG8_SCHED;
;             PG8_STAGE(PG8_SB(0, 1), b2 + hstep, voffB);
;             PG8_WAIT_V(6); PG8_BAR; PG8_MMA(1, 1, At, B1); PG8_BAR;
;             PG8_LDB(B0, 1, 0); PG8_SCHED; PG8_LDA(At, 1, 0); PG8_STAGE(PG8_SA(0, 1), a2 + hstep, voffA);
;             PG8_WAIT_L(8); PG8_BAR; PG8_WAIT_L(0); PG8_MMA(0, 0, At, B0); PG8_BAR; PG8_SCHED;
	s_waitcnt lgkmcnt(0)
	s_setprio 1
	s_waitcnt lgkmcnt(0)
	v_mfma_f32_16x16x32_bf16 v[110:113], v[216:219], v[172:175], v[110:113]
	v_mfma_f32_16x16x32_bf16 v[106:109], v[224:227], v[172:175], v[106:109]
	v_mfma_f32_16x16x32_bf16 v[94:97], v[216:219], v[192:195], v[94:97]
	v_mfma_f32_16x16x32_bf16 v[90:93], v[224:227], v[192:195], v[90:93]
	v_mfma_f32_16x16x32_bf16 v[78:81], v[216:219], v[200:203], v[78:81]
	v_mfma_f32_16x16x32_bf16 v[74:77], v[224:227], v[200:203], v[74:77]
	v_mfma_f32_16x16x32_bf16 v[70:73], v[216:219], v[208:211], v[70:73]
	v_mfma_f32_16x16x32_bf16 v[66:69], v[224:227], v[208:211], v[66:69]
	v_mfma_f32_16x16x32_bf16 v[110:113], v[220:223], v[188:191], v[110:113]
	v_mfma_f32_16x16x32_bf16 v[106:109], v[228:231], v[188:191], v[106:109]
	v_mfma_f32_16x16x32_bf16 v[94:97], v[220:223], v[196:199], v[94:97]
	v_mfma_f32_16x16x32_bf16 v[90:93], v[228:231], v[196:199], v[90:93]
	v_mfma_f32_16x16x32_bf16 v[78:81], v[220:223], v[204:207], v[78:81]
	v_mfma_f32_16x16x32_bf16 v[74:77], v[228:231], v[204:207], v[74:77]
	v_mfma_f32_16x16x32_bf16 v[70:73], v[220:223], v[212:215], v[70:73]
	v_mfma_f32_16x16x32_bf16 v[66:69], v[228:231], v[212:215], v[66:69]
	s_setprio 0
	s_mov_b32 m0, s11
	v_lshl_add_u64 v[236:237], s[70:71], 0, v[146:147]
	s_barrier
	ds_read_b128 v[172:175], v154 offset:16384
	ds_read_b128 v[188:191], v154 offset:17408
	ds_read_b128 v[192:195], v154 offset:18432
	ds_read_b128 v[196:199], v154 offset:19456
	ds_read_b128 v[200:203], v154 offset:20480
	ds_read_b128 v[204:207], v154 offset:21504
	ds_read_b128 v[208:211], v154 offset:22528
	ds_read_b128 v[212:215], v154 offset:23552
	global_load_lds_dwordx4 v[236:237], off
	v_lshl_add_u64 v[238:239], s[70:71], 0, v[142:143]
	s_mov_b32 m0, s74
	s_nop 0
	global_load_lds_dwordx4 v[238:239], off
	s_barrier
	s_waitcnt lgkmcnt(0)
	s_setprio 1
	s_waitcnt lgkmcnt(0)
	v_mfma_f32_16x16x32_bf16 v[62:65], v[156:159], v[172:175], v[62:65]
	v_mfma_f32_16x16x32_bf16 v[58:61], v[164:167], v[172:175], v[58:61]
	v_mfma_f32_16x16x32_bf16 v[54:57], v[156:159], v[192:195], v[54:57]
	v_mfma_f32_16x16x32_bf16 v[50:53], v[164:167], v[192:195], v[50:53]
	v_mfma_f32_16x16x32_bf16 v[38:41], v[156:159], v[200:203], v[38:41]
	v_mfma_f32_16x16x32_bf16 v[34:37], v[164:167], v[200:203], v[34:37]
	v_mfma_f32_16x16x32_bf16 v[22:25], v[156:159], v[208:211], v[22:25]
	v_mfma_f32_16x16x32_bf16 v[18:21], v[164:167], v[208:211], v[18:21]
	v_mfma_f32_16x16x32_bf16 v[62:65], v[160:163], v[188:191], v[62:65]
	v_mfma_f32_16x16x32_bf16 v[58:61], v[168:171], v[188:191], v[58:61]
	v_mfma_f32_16x16x32_bf16 v[54:57], v[160:163], v[196:199], v[54:57]
	v_mfma_f32_16x16x32_bf16 v[50:53], v[168:171], v[196:199], v[50:53]
	v_mfma_f32_16x16x32_bf16 v[38:41], v[160:163], v[204:207], v[38:41]
	v_mfma_f32_16x16x32_bf16 v[34:37], v[168:171], v[204:207], v[34:37]
	v_mfma_f32_16x16x32_bf16 v[22:25], v[160:163], v[212:215], v[22:25]
	v_mfma_f32_16x16x32_bf16 v[18:21], v[168:171], v[212:215], v[18:21]
	s_setprio 0
	s_barrier
	s_add_u32 s20, s66, 0xb0000
	s_addc_u32 s21, s67, 0
	s_add_i32 s19, s22, s9
	v_lshl_add_u64 v[156:157], s[20:21], 0, v[144:145]
	s_mov_b32 m0, s19
	s_nop 0
	global_load_lds_dwordx4 v[156:157], off
	v_lshl_add_u64 v[156:157], s[20:21], 0, v[140:141]
	s_add_i32 m0, s19, 0x2000
	s_nop 0
	global_load_lds_dwordx4 v[156:157], off
	s_waitcnt vmcnt(6)
	s_barrier
	v_add_u32_e32 v155, 0x18010, v152
	ds_read_b128 v[156:159], v155
	ds_read_b128 v[160:163], v155 offset:1024
	ds_read_b128 v[164:167], v155 offset:2048
	ds_read_b128 v[168:171], v155 offset:3072
	s_setprio 1
	v_mfma_f32_16x16x32_bf16 v[46:49], v[216:219], v[172:175], v[46:49]
	v_mfma_f32_16x16x32_bf16 v[42:45], v[224:227], v[172:175], v[42:45]
	v_mfma_f32_16x16x32_bf16 v[30:33], v[216:219], v[192:195], v[30:33]
	v_mfma_f32_16x16x32_bf16 v[26:29], v[224:227], v[192:195], v[26:29]
	v_mfma_f32_16x16x32_bf16 v[14:17], v[216:219], v[200:203], v[14:17]
	v_mfma_f32_16x16x32_bf16 v[10:13], v[224:227], v[200:203], v[10:13]
	v_mfma_f32_16x16x32_bf16 v[4:7], v[216:219], v[208:211], v[4:7]
	v_mfma_f32_16x16x32_bf16 v[0:3], v[224:227], v[208:211], v[0:3]
	v_mfma_f32_16x16x32_bf16 v[46:49], v[220:223], v[188:191], v[46:49]
	v_mfma_f32_16x16x32_bf16 v[42:45], v[228:231], v[188:191], v[42:45]
	v_mfma_f32_16x16x32_bf16 v[30:33], v[220:223], v[196:199], v[30:33]
	v_mfma_f32_16x16x32_bf16 v[26:29], v[228:231], v[196:199], v[26:29]
	v_mfma_f32_16x16x32_bf16 v[14:17], v[220:223], v[204:207], v[14:17]
	v_mfma_f32_16x16x32_bf16 v[10:13], v[228:231], v[204:207], v[10:13]
	v_mfma_f32_16x16x32_bf16 v[4:7], v[220:223], v[212:215], v[4:7]
	v_mfma_f32_16x16x32_bf16 v[0:3], v[228:231], v[212:215], v[0:3]
	s_setprio 0
	s_add_i32 s19, 16, 0x18000
	v_add_u32_e32 v155, s19, v152
	s_barrier
	s_add_u32 s20, s70, 0xb0000
	s_addc_u32 s21, s71, 0
	s_mov_b32 m0, s12
	v_lshl_add_u64 v[216:217], s[20:21], 0, v[146:147]
	ds_read_b128 v[172:175], v154 offset:32768
	ds_read_b128 v[188:191], v154 offset:33792
	ds_read_b128 v[192:195], v154 offset:34816
	ds_read_b128 v[196:199], v154 offset:35840
	ds_read_b128 v[200:203], v154 offset:36864
	ds_read_b128 v[204:207], v154 offset:37888
	ds_read_b128 v[208:211], v154 offset:38912
	ds_read_b128 v[212:215], v154 offset:39936
	global_load_lds_dwordx4 v[216:217], off
	v_lshl_add_u64 v[216:217], s[20:21], 0, v[142:143]
	s_mov_b32 m0, s13
	s_nop 0
	global_load_lds_dwordx4 v[216:217], off
	s_waitcnt lgkmcnt(8)
	s_barrier
; #define PG8_STAGE(bufoff, gbase, voff) do { _Pragma("unroll") for (int _i = 0; _i < 2; ++_i) \
;         __builtin_amdgcn_global_load_lds((const unsigned*)((const char*)(gbase) + (voff)[_i]), (LAS unsigned*)(lds + (bufoff) + ldsw + _i * 8192), 16, 0, 0); } while (0)
; #define PG8_LDA(dst, b, h) do { _Pragma("unroll") for (int m = 0; m < 4; ++m) _Pragma("unroll") for (int k = 0; k < 2; ++k) dst[m][k] = *(const LAS bf16x8*)(lds + PG8_SA(b, h) + aoff + m * 2048 + k * 1024); } while (0)
; #define PG8_LDB(dst, b, h) do { _Pragma("unroll") for (int n = 0; n < 2; ++n) _Pragma("unroll") for (int k = 0; k < 2; ++k) dst[n][k] = *(const LAS bf16x8*)(lds + PG8_SB(b, h) + boff + n * 2048 + k * 1024); } while (0)
; #define PG8_MMA(ai, bj, At, Bt) do { __builtin_amdgcn_s_setprio(1); _Pragma("unroll") for (int m = 0; m < 4; ++m) _Pragma("unroll") for (int n = 0; n < 2; ++n) _Pragma("unroll") for (int k = 0; k < 2; ++k) \
;         acc[ai][bj][m][n] = __builtin_amdgcn_mfma_f32_16x16x32_bf16(Bt[n][k], At[m][k], acc[ai][bj][m][n], 0, 0, 0); __builtin_amdgcn_s_setprio(0); } while (0)
; #define PG8_WAIT_L(n) asm volatile("s_waitcnt lgkmcnt(" #n ")" ::: "memory")
; #define PG8_BAR __builtin_amdgcn_s_barrier()
; #define PG8_SCHED __builtin_amdgcn_sched_barrier(0)
; template <class Epi, class Sched>
; __device__ __forceinline__ void gemm_phase(LAS unsigned char* lds, const Gemm g, const Sched& S, const Epi& E) {
;     ...
;             PG8_WAIT_L(8); PG8_BAR; PG8_WAIT_L(0); PG8_MMA(0, 0, At, B0); PG8_BAR; PG8_SCHED;
;             PG8_LDB(B1, 1, 1); PG8_STAGE(PG8_SB(1, 0), b3, voffB);
;             PG8_BAR; PG8_WAIT_L(0); PG8_MMA(0, 1, At, B1); PG8_BAR;
;             PG8_LDA(At, 1, 1); PG8_STAGE(PG8_SA(1, 0), a3, voffA);
;             PG8_BAR; PG8_WAIT_L(0); PG8_MMA(1, 0, At, B0); PG8_BAR; PG8_SCHED;
;             PG8_STAGE(PG8_SB(1, 1), b3 + hstep, voffB);
	s_waitcnt lgkmcnt(0)
	s_setprio 1
	s_waitcnt lgkmcnt(0)
	v_mfma_f32_16x16x32_bf16 v[126:129], v[156:159], v[172:175], v[126:129]
	v_mfma_f32_16x16x32_bf16 v[122:125], v[164:167], v[172:175], v[122:125]
	v_mfma_f32_16x16x32_bf16 v[118:121], v[156:159], v[192:195], v[118:121]
	v_mfma_f32_16x16x32_bf16 v[114:117], v[164:167], v[192:195], v[114:117]
	v_mfma_f32_16x16x32_bf16 v[102:105], v[156:159], v[200:203], v[102:105]
	v_mfma_f32_16x16x32_bf16 v[98:101], v[164:167], v[200:203], v[98:101]
	v_mfma_f32_16x16x32_bf16 v[86:89], v[156:159], v[208:211], v[86:89]
	v_mfma_f32_16x16x32_bf16 v[82:85], v[164:167], v[208:211], v[82:85]
	v_mfma_f32_16x16x32_bf16 v[126:129], v[160:163], v[188:191], v[126:129]
	v_mfma_f32_16x16x32_bf16 v[122:125], v[168:171], v[188:191], v[122:125]
	v_mfma_f32_16x16x32_bf16 v[118:121], v[160:163], v[196:199], v[118:121]
	v_mfma_f32_16x16x32_bf16 v[114:117], v[168:171], v[196:199], v[114:117]
	v_mfma_f32_16x16x32_bf16 v[102:105], v[160:163], v[204:207], v[102:105]
	v_mfma_f32_16x16x32_bf16 v[98:101], v[168:171], v[204:207], v[98:101]
	v_mfma_f32_16x16x32_bf16 v[86:89], v[160:163], v[212:215], v[86:89]
	v_mfma_f32_16x16x32_bf16 v[82:85], v[168:171], v[212:215], v[82:85]
	s_setprio 0
	s_barrier
	s_add_i32 s22, 16, 0x1c000
	s_add_i32 s19, s19, s9
	v_add_u32_e32 v155, s22, v152
	v_lshl_add_u64 v[232:233], v[232:233], 0, s[94:95]
	s_mov_b32 m0, s19
	ds_read_b128 v[216:219], v155
	ds_read_b128 v[220:223], v155 offset:1024
	ds_read_b128 v[224:227], v155 offset:2048
	ds_read_b128 v[228:231], v155 offset:3072
	global_load_lds_dwordx4 v[232:233], off
	v_lshl_add_u64 v[232:233], v[234:235], 0, s[94:95]
	s_add_i32 m0, s19, 0x2000
	s_nop 0
	global_load_lds_dwordx4 v[232:233], off
	s_barrier
	s_waitcnt lgkmcnt(0)
	s_setprio 1
	s_waitcnt lgkmcnt(0)
	v_mfma_f32_16x16x32_bf16 v[110:113], v[216:219], v[172:175], v[110:113]
	v_mfma_f32_16x16x32_bf16 v[106:109], v[224:227], v[172:175], v[106:109]
	v_mfma_f32_16x16x32_bf16 v[94:97], v[216:219], v[192:195], v[94:97]
	v_mfma_f32_16x16x32_bf16 v[90:93], v[224:227], v[192:195], v[90:93]
	v_mfma_f32_16x16x32_bf16 v[78:81], v[216:219], v[200:203], v[78:81]
	v_mfma_f32_16x16x32_bf16 v[74:77], v[224:227], v[200:203], v[74:77]
	v_mfma_f32_16x16x32_bf16 v[70:73], v[216:219], v[208:211], v[70:73]
	v_mfma_f32_16x16x32_bf16 v[66:69], v[224:227], v[208:211], v[66:69]
	v_mfma_f32_16x16x32_bf16 v[110:113], v[220:223], v[188:191], v[110:113]
	v_mfma_f32_16x16x32_bf16 v[106:109], v[228:231], v[188:191], v[106:109]
	v_mfma_f32_16x16x32_bf16 v[94:97], v[220:223], v[196:199], v[94:97]
	v_mfma_f32_16x16x32_bf16 v[90:93], v[228:231], v[196:199], v[90:93]
	v_mfma_f32_16x16x32_bf16 v[78:81], v[220:223], v[204:207], v[78:81]
	v_mfma_f32_16x16x32_bf16 v[74:77], v[228:231], v[204:207], v[74:77]
	v_mfma_f32_16x16x32_bf16 v[70:73], v[220:223], v[212:215], v[70:73]
	v_mfma_f32_16x16x32_bf16 v[66:69], v[228:231], v[212:215], v[66:69]
	s_setprio 0
	s_mov_b32 m0, s14
	v_lshl_add_u64 v[232:233], v[236:237], 0, s[94:95]
	s_barrier
	ds_read_b128 v[172:175], v154 offset:49152
	ds_read_b128 v[188:191], v154 offset:50176
	ds_read_b128 v[192:195], v154 offset:51200
	ds_read_b128 v[196:199], v154 offset:52224
	ds_read_b128 v[200:203], v154 offset:53248
	ds_read_b128 v[204:207], v154 offset:54272
	ds_read_b128 v[208:211], v154 offset:55296
	ds_read_b128 v[212:215], v154 offset:56320
	global_load_lds_dwordx4 v[232:233], off
	v_lshl_add_u64 v[232:233], v[238:239], 0, s[94:95]
	s_mov_b32 m0, s15
	s_nop 0
	global_load_lds_dwordx4 v[232:233], off
	s_barrier
	s_waitcnt lgkmcnt(0)
	s_setprio 1
	s_waitcnt lgkmcnt(0)
	v_mfma_f32_16x16x32_bf16 v[62:65], v[156:159], v[172:175], v[62:65]
	v_mfma_f32_16x16x32_bf16 v[58:61], v[164:167], v[172:175], v[58:61]
	v_mfma_f32_16x16x32_bf16 v[54:57], v[156:159], v[192:195], v[54:57]
	v_mfma_f32_16x16x32_bf16 v[50:53], v[164:167], v[192:195], v[50:53]
	v_mfma_f32_16x16x32_bf16 v[38:41], v[156:159], v[200:203], v[38:41]
	v_mfma_f32_16x16x32_bf16 v[34:37], v[164:167], v[200:203], v[34:37]
	v_mfma_f32_16x16x32_bf16 v[22:25], v[156:159], v[208:211], v[22:25]
	v_mfma_f32_16x16x32_bf16 v[18:21], v[164:167], v[208:211], v[18:21]
	v_mfma_f32_16x16x32_bf16 v[62:65], v[160:163], v[188:191], v[62:65]
	v_mfma_f32_16x16x32_bf16 v[58:61], v[168:171], v[188:191], v[58:61]
	v_mfma_f32_16x16x32_bf16 v[54:57], v[160:163], v[196:199], v[54:57]
	v_mfma_f32_16x16x32_bf16 v[50:53], v[168:171], v[196:199], v[50:53]
	v_mfma_f32_16x16x32_bf16 v[38:41], v[160:163], v[204:207], v[38:41]
	v_mfma_f32_16x16x32_bf16 v[34:37], v[168:171], v[204:207], v[34:37]
	v_mfma_f32_16x16x32_bf16 v[22:25], v[160:163], v[212:215], v[22:25]
	v_mfma_f32_16x16x32_bf16 v[18:21], v[168:171], v[212:215], v[18:21]
	s_setprio 0
	s_barrier
	s_add_u32 s20, s66, 0xb0080
	s_addc_u32 s21, s67, 0
	s_add_i32 s19, s22, s9
	v_lshl_add_u64 v[156:157], s[20:21], 0, v[144:145]
	s_mov_b32 m0, s19
	s_nop 0
	global_load_lds_dwordx4 v[156:157], off
	v_lshl_add_u64 v[156:157], s[20:21], 0, v[140:141]
	s_add_i32 m0, s19, 0x2000
	s_nop 0
	global_load_lds_dwordx4 v[156:157], off
	s_waitcnt vmcnt(6)
	s_barrier
; __device__ __forceinline__ unsigned pk_bf16(float a, float b) { f32x2 v = {a, b}; bf2_t r = __builtin_convertvector(v, bf2_t); return __builtin_bit_cast(unsigned, r); }
; #define PG8_MMA(ai, bj, At, Bt) do { __builtin_amdgcn_s_setprio(1); _Pragma("unroll") for (int m = 0; m < 4; ++m) _Pragma("unroll") for (int n = 0; n < 2; ++n) _Pragma("unroll") for (int k = 0; k < 2; ++k) \
;         acc[ai][bj][m][n] = __builtin_amdgcn_mfma_f32_16x16x32_bf16(Bt[n][k], At[m][k], acc[ai][bj][m][n], 0, 0, 0); __builtin_amdgcn_s_setprio(0); } while (0)
; #define PG8_WAIT_V(n) asm volatile("s_waitcnt vmcnt(" #n ")" ::: "memory")
; #define PG8_BAR __builtin_amdgcn_s_barrier()
;     __device__ __forceinline__ void operator()(const f32x4 (&acc)[2][2][4][2], const Unit& u, int wr, int wc, int fr, int fq) const {
;         const int row0 = u.pm * BM + wr * 64 + fr; int colt = u.pn * BM; bf16_t* base = O;
;         if (split_cols) { const int t = colt / split_cols; base += (size_t)t * split_stride; colt -= t * split_cols; }
;         const int col0 = colt + wc * 32 + 8 * fq;
; #pragma unroll
;         for (int ai = 0; ai < 2; ++ai)
; #pragma unroll
;             for (int m = 0; m < 4; ++m) { const int row = row0 + ai * HALF + m * 16;
;                 bf16_t* rowp = slot_stride ? base + (size_t)(colt >> 7) * slot_stride + (size_t)row * 128 + wc * 32 + 8 * fq : base + (size_t)row * ldc + col0;
; #pragma unroll
;                 for (int bj = 0; bj < 2; ++bj) { const f32x4 v0 = acc[ai][bj][m][0], v1 = acc[ai][bj][m][1];
;                     u32x4 w; w.x = pk_bf16(v0[0], v0[1]); w.y = pk_bf16(v0[2], v0[3]); w.z = pk_bf16(v1[0], v1[1]); w.w = pk_bf16(v1[2], v1[3]);
;                     *(u32x4*)(rowp + (slot_stride ? (size_t)bj * slot_stride : (size_t)bj * HALF)) = w; } }
; template <class Epi, class Sched>
; __device__ __forceinline__ void gemm_phase(LAS unsigned char* lds, const Gemm g, const Sched& S, const Epi& E) {
;     ...
;             PG8_WAIT_V(6); PG8_BAR; PG8_MMA(1, 1, At, B1); PG8_BAR;
;         }
;         E(acc, cur, wr, wc, fr, fq); S.done(cur);
;         if (!has_next) break;
	v_add_u32_e32 v155, 0x10010, v152
	ds_read_b128 v[156:159], v155
	ds_read_b128 v[160:163], v155 offset:1024
	ds_read_b128 v[164:167], v155 offset:2048
	ds_read_b128 v[168:171], v155 offset:3072
	s_setprio 1
	v_mfma_f32_16x16x32_bf16 v[46:49], v[216:219], v[172:175], v[46:49]
	v_mfma_f32_16x16x32_bf16 v[42:45], v[224:227], v[172:175], v[42:45]
	v_mfma_f32_16x16x32_bf16 v[30:33], v[216:219], v[192:195], v[30:33]
	v_mfma_f32_16x16x32_bf16 v[26:29], v[224:227], v[192:195], v[26:29]
	v_mfma_f32_16x16x32_bf16 v[14:17], v[216:219], v[200:203], v[14:17]
	v_mfma_f32_16x16x32_bf16 v[10:13], v[224:227], v[200:203], v[10:13]
	v_mfma_f32_16x16x32_bf16 v[4:7], v[216:219], v[208:211], v[4:7]
	v_mfma_f32_16x16x32_bf16 v[0:3], v[224:227], v[208:211], v[0:3]
	v_mfma_f32_16x16x32_bf16 v[46:49], v[220:223], v[188:191], v[46:49]
	v_mfma_f32_16x16x32_bf16 v[42:45], v[228:231], v[188:191], v[42:45]
	v_mfma_f32_16x16x32_bf16 v[30:33], v[220:223], v[196:199], v[30:33]
	v_mfma_f32_16x16x32_bf16 v[26:29], v[228:231], v[196:199], v[26:29]
	v_mfma_f32_16x16x32_bf16 v[14:17], v[220:223], v[204:207], v[14:17]
	v_mfma_f32_16x16x32_bf16 v[10:13], v[228:231], v[204:207], v[10:13]
	v_mfma_f32_16x16x32_bf16 v[4:7], v[220:223], v[212:215], v[4:7]
	v_mfma_f32_16x16x32_bf16 v[0:3], v[228:231], v[212:215], v[0:3]
	s_setprio 0
	s_add_i32 s18, s18, 2
	s_add_u32 s16, s16, 0x100
	s_addc_u32 s17, s17, 0
	s_cmp_gt_u32 s18, 41
	s_mov_b64 s[42:43], s[72:73]
	s_barrier
	s_cbranch_scc0 .LBB0_825
	s_waitcnt lgkmcnt(0)
	v_lshl_add_u32 v156, s78, 8, v9
	v_lshl_or_b32 v158, s75, 8, v153
	v_readlane_b32 s16, v244, 38
	v_ashrrev_i32_e32 v159, 31, v158
	v_readlane_b32 s17, v244, 39
	v_ashrrev_i32_e32 v157, 31, v156
	v_lshlrev_b64 v[160:161], 11, v[156:157]
	v_lshl_add_u64 v[158:159], v[158:159], 1, s[16:17]
	v_lshl_add_u64 v[160:161], v[158:159], 0, v[160:161]
	s_mov_b64 s[16:17], 0x40000
	v_cvt_pk_bf16_f32 v70, v70, v71
	v_cvt_pk_bf16_f32 v71, v72, v73
	v_cvt_pk_bf16_f32 v72, v66, v67
	v_lshl_add_u64 v[66:67], v[160:161], 0, s[16:17]
	s_mov_b32 s16, 0x40000
	v_cvt_pk_bf16_f32 v62, v62, v63
	v_cvt_pk_bf16_f32 v63, v64, v65
	v_cvt_pk_bf16_f32 v64, v58, v59
	v_add_co_u32_e32 v58, vcc, s16, v160
	v_cvt_pk_bf16_f32 v46, v46, v47
	v_cvt_pk_bf16_f32 v47, v48, v49
	v_cvt_pk_bf16_f32 v48, v42, v43
	v_cvt_pk_bf16_f32 v49, v44, v45
	s_mov_b64 s[16:17], 0x48000
	v_addc_co_u32_e32 v59, vcc, 0, v161, vcc
	global_store_dwordx4 v[66:67], v[46:49], off offset:256
	v_cvt_pk_bf16_f32 v30, v30, v31
	v_cvt_pk_bf16_f32 v31, v32, v33
	v_lshl_add_u64 v[46:47], v[160:161], 0, s[16:17]
	s_mov_b32 s16, 0x48000
	v_add_co_u32_e32 v48, vcc, s16, v160
	v_cvt_pk_bf16_f32 v32, v26, v27
	v_cvt_pk_bf16_f32 v33, v28, v29
	s_mov_b64 s[16:17], 0x50000
	v_cvt_pk_bf16_f32 v110, v110, v111
	v_cvt_pk_bf16_f32 v111, v112, v113
	v_cvt_pk_bf16_f32 v112, v106, v107
	v_or_b32_e32 v106, 16, v156
	v_addc_co_u32_e32 v49, vcc, 0, v161, vcc
	global_store_dwordx4 v[46:47], v[30:33], off offset:256
	v_ashrrev_i32_e32 v107, 31, v106
	v_cvt_pk_bf16_f32 v94, v94, v95
	v_lshl_add_u64 v[30:31], v[160:161], 0, s[16:17]
	s_mov_b32 s16, 0x50000
	v_cvt_pk_bf16_f32 v95, v96, v97
	v_cvt_pk_bf16_f32 v96, v90, v91
	v_or_b32_e32 v90, 32, v156
	v_add_co_u32_e32 v32, vcc, s16, v160
	v_cvt_pk_bf16_f32 v14, v14, v15
	v_cvt_pk_bf16_f32 v15, v16, v17
	v_cvt_pk_bf16_f32 v16, v10, v11
	v_cvt_pk_bf16_f32 v17, v12, v13
	s_mov_b64 s[16:17], 0x58000
	v_cvt_pk_bf16_f32 v113, v108, v109
	v_lshlrev_b64 v[106:107], 11, v[106:107]
	v_ashrrev_i32_e32 v91, 31, v90
	v_cvt_pk_bf16_f32 v78, v78, v79
	v_cvt_pk_bf16_f32 v79, v80, v81
	v_cvt_pk_bf16_f32 v80, v74, v75
	v_or_b32_e32 v74, 48, v156
	v_addc_co_u32_e32 v33, vcc, 0, v161, vcc
	global_store_dwordx4 v[30:31], v[14:17], off offset:256
	global_store_dwordx4 v[160:161], v[110:113], off offset:256
	v_cvt_pk_bf16_f32 v97, v92, v93
	v_lshl_add_u64 v[14:15], v[160:161], 0, s[16:17]
	s_mov_b32 s16, 0x58000
	v_lshl_add_u64 v[110:111], v[158:159], 0, v[106:107]
	v_lshlrev_b64 v[90:91], 11, v[90:91]
	v_ashrrev_i32_e32 v75, 31, v74
	v_add_co_u32_e32 v16, vcc, s16, v160
	global_store_dwordx4 v[110:111], v[94:97], off offset:256
	v_cvt_pk_bf16_f32 v81, v76, v77
	v_lshlrev_b64 v[74:75], 11, v[74:75]
	v_lshl_add_u64 v[94:95], v[158:159], 0, v[90:91]
	v_addc_co_u32_e32 v17, vcc, 0, v161, vcc
	v_readlane_b32 s70, v244, 55
	v_cvt_pk_bf16_f32 v126, v126, v127
	v_cvt_pk_bf16_f32 v127, v128, v129
	v_cvt_pk_bf16_f32 v128, v122, v123
	v_cvt_pk_bf16_f32 v129, v124, v125
	v_cvt_pk_bf16_f32 v106, v118, v119
	v_cvt_pk_bf16_f32 v107, v120, v121
	v_cvt_pk_bf16_f32 v108, v114, v115
	v_cvt_pk_bf16_f32 v109, v116, v117
	v_cvt_pk_bf16_f32 v90, v102, v103
	v_cvt_pk_bf16_f32 v91, v104, v105
	v_cvt_pk_bf16_f32 v92, v98, v99
	v_cvt_pk_bf16_f32 v93, v100, v101
	global_store_dwordx4 v[94:95], v[78:81], off offset:256
	v_cvt_pk_bf16_f32 v76, v82, v83
	v_cvt_pk_bf16_f32 v77, v84, v85
	v_lshl_add_u64 v[78:79], v[158:159], 0, v[74:75]
	v_cvt_pk_bf16_f32 v74, v86, v87
	v_cvt_pk_bf16_f32 v75, v88, v89
	v_cvt_pk_bf16_f32 v73, v68, v69
	v_cvt_pk_bf16_f32 v65, v60, v61
	v_cvt_pk_bf16_f32 v42, v54, v55
	v_cvt_pk_bf16_f32 v43, v56, v57
	v_cvt_pk_bf16_f32 v44, v50, v51
	v_cvt_pk_bf16_f32 v45, v52, v53
	v_cvt_pk_bf16_f32 v26, v38, v39
	v_cvt_pk_bf16_f32 v27, v40, v41
	v_cvt_pk_bf16_f32 v28, v34, v35
	v_cvt_pk_bf16_f32 v29, v36, v37
	v_cvt_pk_bf16_f32 v10, v22, v23
	v_cvt_pk_bf16_f32 v11, v24, v25
	v_cvt_pk_bf16_f32 v12, v18, v19
	v_cvt_pk_bf16_f32 v13, v20, v21
	v_cvt_pk_bf16_f32 v4, v4, v5
	v_cvt_pk_bf16_f32 v5, v6, v7
	v_cvt_pk_bf16_f32 v6, v0, v1
	v_cvt_pk_bf16_f32 v7, v2, v3
	s_and_b64 vcc, exec, s[38:39]
	s_mov_b32 s75, s85
	s_mov_b32 s78, s88
	s_mov_b64 s[72:73], s[0:1]
	s_mov_b64 s[42:43], s[40:41]
	v_readlane_b32 s71, v244, 56
	global_store_dwordx4 v[160:161], v[126:129], off
	global_store_dwordx4 v[110:111], v[106:109], off
	global_store_dwordx4 v[94:95], v[90:93], off
	global_store_dwordx4 v[78:79], v[74:77], off
	global_store_dwordx4 v[78:79], v[70:73], off offset:256
	global_store_dwordx4 v[58:59], v[62:65], off
	global_store_dwordx4 v[48:49], v[42:45], off
	global_store_dwordx4 v[32:33], v[26:29], off
	global_store_dwordx4 v[16:17], v[10:13], off
	global_store_dwordx4 v[14:15], v[4:7], off offset:256
	s_cbranch_vccz .LBB0_818
	s_waitcnt vmcnt(0)
	v_readlane_b32 s16, v244, 51
	s_cmpk_gt_u32 s6, 0xff
	v_readlane_b32 s17, v244, 52
	s_cbranch_scc1 .LBB0_829
	s_barrier
